# K-loop s_setprio flips removed (all 8 GEMM loops)
# speedup vs baseline: 1.0798x; 1.0798x over previous
.LBB0_304:
	s_waitcnt lgkmcnt(0)
	ds_read_b128 v[2:5], v234
	ds_read_b128 v[6:9], v234 offset:1024
	ds_read_b128 v[10:13], v234 offset:2048
	ds_read_b128 v[14:17], v234 offset:3072
	ds_read_b128 v[18:21], v235
	ds_read_b128 v[22:25], v235 offset:1024
	ds_read_b128 v[26:29], v235 offset:2048
	ds_read_b128 v[30:33], v235 offset:3072
	s_add_u32 s6, s4, 0xfff80080
	s_addc_u32 s7, s5, -1
	s_cmp_eq_u32 s80, 28
	s_cselect_b32 s9, s35, s7
	s_cselect_b32 s8, s52, s6
	s_cselect_b32 s7, s31, s79
	s_cselect_b32 s6, s77, s78
	v_lshl_add_u64 v[214:215], s[4:5], 0, v[206:207]
	s_add_i32 m0, s43, 0xc000
	ds_read_b128 v[98:101], v236
	ds_read_b128 v[102:105], v236 offset:1024
	ds_read_b128 v[106:109], v236 offset:2048
	ds_read_b128 v[110:113], v236 offset:3072
	ds_read_b128 v[178:181], v236 offset:4096
	ds_read_b128 v[182:185], v236 offset:5120
	ds_read_b128 v[186:189], v236 offset:6144
	ds_read_b128 v[190:193], v236 offset:7168
	global_load_lds_dwordx4 v[214:215], off
	v_lshl_add_u64 v[214:215], s[4:5], 0, v[208:209]
	s_add_i32 m0, s43, 0xe000
	s_nop 0
	global_load_lds_dwordx4 v[214:215], off
	s_waitcnt vmcnt(8)
	s_waitcnt lgkmcnt(0)
	s_barrier
	s_waitcnt lgkmcnt(0)
	v_mfma_i32_16x16x64_i8 v[174:177], v[2:5], v[98:101], v[174:177]
	v_mfma_i32_16x16x64_i8 v[170:173], v[10:13], v[98:101], v[170:173]
	v_mfma_i32_16x16x64_i8 v[158:161], v[2:5], v[106:109], v[158:161]
	v_mfma_i32_16x16x64_i8 v[154:157], v[10:13], v[106:109], v[154:157]
	v_mfma_i32_16x16x64_i8 v[142:145], v[2:5], v[178:181], v[142:145]
	v_mfma_i32_16x16x64_i8 v[138:141], v[10:13], v[178:181], v[138:141]
	v_mfma_i32_16x16x64_i8 v[126:129], v[2:5], v[186:189], v[126:129]
	v_mfma_i32_16x16x64_i8 v[122:125], v[10:13], v[186:189], v[122:125]
	v_mfma_i32_16x16x64_i8 v[174:177], v[6:9], v[102:105], v[174:177]
	v_mfma_i32_16x16x64_i8 v[170:173], v[14:17], v[102:105], v[170:173]
	v_mfma_i32_16x16x64_i8 v[158:161], v[6:9], v[110:113], v[158:161]
	v_mfma_i32_16x16x64_i8 v[154:157], v[14:17], v[110:113], v[154:157]
	v_mfma_i32_16x16x64_i8 v[142:145], v[6:9], v[182:185], v[142:145]
	v_mfma_i32_16x16x64_i8 v[138:141], v[14:17], v[182:185], v[138:141]
	v_mfma_i32_16x16x64_i8 v[126:129], v[6:9], v[190:193], v[126:129]
	v_mfma_i32_16x16x64_i8 v[122:125], v[14:17], v[190:193], v[122:125]
	v_mfma_i32_16x16x64_i8 v[166:169], v[18:21], v[98:101], v[166:169]
	v_mfma_i32_16x16x64_i8 v[98:101], v[26:29], v[98:101], v[162:165]
	v_mfma_i32_16x16x64_i8 v[166:169], v[22:25], v[102:105], v[166:169]
	v_mfma_i32_16x16x64_i8 v[98:101], v[30:33], v[102:105], v[98:101]
	v_mfma_i32_16x16x64_i8 v[102:105], v[18:21], v[106:109], v[150:153]
	v_mfma_i32_16x16x64_i8 v[106:109], v[26:29], v[106:109], v[146:149]
	v_mfma_i32_16x16x64_i8 v[130:133], v[26:29], v[178:181], v[130:133]
	v_mfma_i32_16x16x64_i8 v[118:121], v[18:21], v[186:189], v[118:121]
	v_mfma_i32_16x16x64_i8 v[114:117], v[26:29], v[186:189], v[114:117]
	v_mfma_i32_16x16x64_i8 v[102:105], v[22:25], v[110:113], v[102:105]
	v_mfma_i32_16x16x64_i8 v[106:109], v[30:33], v[110:113], v[106:109]
	v_mfma_i32_16x16x64_i8 v[110:113], v[18:21], v[178:181], v[134:137]
	v_mfma_i32_16x16x64_i8 v[130:133], v[30:33], v[182:185], v[130:133]
	v_mfma_i32_16x16x64_i8 v[118:121], v[22:25], v[190:193], v[118:121]
	v_mfma_i32_16x16x64_i8 v[114:117], v[30:33], v[190:193], v[114:117]
	v_mfma_i32_16x16x64_i8 v[110:113], v[22:25], v[182:185], v[110:113]
	s_barrier
	s_add_i32 s81, s70, s41
	v_lshl_add_u64 v[226:227], s[6:7], 0, v[196:197]
	s_mov_b32 m0, s81
	ds_read_b128 v[134:137], v236 offset:16384
	ds_read_b128 v[146:149], v236 offset:17408
	ds_read_b128 v[150:153], v236 offset:18432
	ds_read_b128 v[162:165], v236 offset:19456
	ds_read_b128 v[178:181], v236 offset:20480
	ds_read_b128 v[182:185], v236 offset:21504
	ds_read_b128 v[186:189], v236 offset:22528
	ds_read_b128 v[190:193], v236 offset:23552
	global_load_lds_dwordx4 v[226:227], off
	s_add_i32 m0, s81, 0x2000
	s_add_u32 s82, s6, 0x80000
	v_lshl_add_u64 v[244:245], s[6:7], 0, v[198:199]
	s_addc_u32 s83, s7, 0
	s_add_i32 s81, s71, s41
	global_load_lds_dwordx4 v[244:245], off
	v_lshl_add_u64 v[214:215], s[82:83], 0, v[196:197]
	s_mov_b32 m0, s81
	v_lshl_add_u64 v[246:247], s[8:9], 0, v[196:197]
	global_load_lds_dwordx4 v[214:215], off
	v_lshl_add_u64 v[214:215], s[82:83], 0, v[198:199]
	s_add_i32 m0, s81, 0x2000
	v_lshl_add_u64 v[248:249], s[8:9], 0, v[198:199]
	global_load_lds_dwordx4 v[214:215], off
	s_mov_b32 m0, s43
	s_nop 0
	global_load_lds_dwordx4 v[246:247], off
	s_mov_b32 m0, s57
	s_nop 0
	global_load_lds_dwordx4 v[248:249], off
	s_waitcnt vmcnt(8)
	s_waitcnt lgkmcnt(0)
	s_barrier
	s_waitcnt lgkmcnt(0)
	v_mfma_i32_16x16x64_i8 v[94:97], v[2:5], v[134:137], v[94:97]
	v_mfma_i32_16x16x64_i8 v[90:93], v[10:13], v[134:137], v[90:93]
	v_mfma_i32_16x16x64_i8 v[78:81], v[2:5], v[150:153], v[78:81]
	v_mfma_i32_16x16x64_i8 v[74:77], v[10:13], v[150:153], v[74:77]
	v_mfma_i32_16x16x64_i8 v[62:65], v[2:5], v[178:181], v[62:65]
	v_mfma_i32_16x16x64_i8 v[58:61], v[10:13], v[178:181], v[58:61]
	v_mfma_i32_16x16x64_i8 v[2:5], v[2:5], v[186:189], v[46:49]
	v_mfma_i32_16x16x64_i8 v[94:97], v[6:9], v[146:149], v[94:97]
	v_mfma_i32_16x16x64_i8 v[90:93], v[14:17], v[146:149], v[90:93]
	v_mfma_i32_16x16x64_i8 v[78:81], v[6:9], v[162:165], v[78:81]
	v_mfma_i32_16x16x64_i8 v[74:77], v[14:17], v[162:165], v[74:77]
	v_mfma_i32_16x16x64_i8 v[62:65], v[6:9], v[182:185], v[62:65]
	v_mfma_i32_16x16x64_i8 v[58:61], v[14:17], v[182:185], v[58:61]
	v_mfma_i32_16x16x64_i8 v[2:5], v[6:9], v[190:193], v[2:5]
	v_mfma_i32_16x16x64_i8 v[6:9], v[10:13], v[186:189], v[42:45]
	v_mfma_i32_16x16x64_i8 v[6:9], v[14:17], v[190:193], v[6:9]
	v_mfma_i32_16x16x64_i8 v[42:45], v[18:21], v[150:153], v[70:73]
	v_mfma_i32_16x16x64_i8 v[70:73], v[22:25], v[162:165], v[42:45]
	v_mfma_i32_16x16x64_i8 v[42:45], v[26:29], v[150:153], v[66:69]
	v_mfma_i32_16x16x64_i8 v[66:69], v[30:33], v[162:165], v[42:45]
	v_mfma_i32_16x16x64_i8 v[42:45], v[18:21], v[178:181], v[54:57]
	v_mfma_i32_16x16x64_i8 v[10:13], v[18:21], v[134:137], v[86:89]
	v_mfma_i32_16x16x64_i8 v[54:57], v[22:25], v[182:185], v[42:45]
	v_mfma_i32_16x16x64_i8 v[42:45], v[26:29], v[178:181], v[50:53]
	v_mfma_i32_16x16x64_i8 v[18:21], v[18:21], v[186:189], v[38:41]
	v_mfma_i32_16x16x64_i8 v[10:13], v[22:25], v[146:149], v[10:13]
	v_mfma_i32_16x16x64_i8 v[14:17], v[26:29], v[134:137], v[82:85]
	v_mfma_i32_16x16x64_i8 v[50:53], v[30:33], v[182:185], v[42:45]
	v_mfma_i32_16x16x64_i8 v[18:21], v[22:25], v[190:193], v[18:21]
	v_mfma_i32_16x16x64_i8 v[22:25], v[26:29], v[186:189], v[34:37]
	v_mfma_i32_16x16x64_i8 v[14:17], v[30:33], v[146:149], v[14:17]
	v_mfma_i32_16x16x64_i8 v[22:25], v[30:33], v[190:193], v[22:25]
	s_barrier
	s_add_i32 s81, 0, 0x18000
	s_add_i32 s82, 0, 0x1c000
	v_add_u32_e32 v38, s81, v229
	v_add_u32_e32 v42, s82, v229
	ds_read_b128 v[26:29], v38
	ds_read_b128 v[30:33], v38 offset:1024
	ds_read_b128 v[34:37], v38 offset:2048
	ds_read_b128 v[38:41], v38 offset:3072
	ds_read_b128 v[178:181], v42
	ds_read_b128 v[182:185], v42 offset:1024
	ds_read_b128 v[186:189], v42 offset:2048
	ds_read_b128 v[190:193], v42 offset:3072
	s_add_u32 s8, s8, 0x80000
	s_addc_u32 s9, s9, 0
	s_mov_b32 m0, s60
	v_lshl_add_u64 v[134:135], s[8:9], 0, v[196:197]
	ds_read_b128 v[42:45], v236 offset:32768
	ds_read_b128 v[46:49], v236 offset:33792
	ds_read_b128 v[82:85], v236 offset:34816
	ds_read_b128 v[86:89], v236 offset:35840
	ds_read_b128 v[214:217], v236 offset:36864
	ds_read_b128 v[218:221], v236 offset:37888
	ds_read_b128 v[222:225], v236 offset:38912
	ds_read_b128 v[240:243], v236 offset:39936
	global_load_lds_dwordx4 v[134:135], off
	v_lshl_add_u64 v[134:135], s[8:9], 0, v[198:199]
	s_mov_b32 m0, s61
	s_nop 0
	global_load_lds_dwordx4 v[134:135], off
	s_waitcnt vmcnt(8)
	s_waitcnt lgkmcnt(0)
	s_barrier
	s_waitcnt lgkmcnt(0)
	v_mfma_i32_16x16x64_i8 v[134:137], v[26:29], v[42:45], v[174:177]
	v_mfma_i32_16x16x64_i8 v[174:177], v[30:33], v[46:49], v[134:137]
	v_mfma_i32_16x16x64_i8 v[134:137], v[34:37], v[42:45], v[170:173]
	v_mfma_i32_16x16x64_i8 v[170:173], v[38:41], v[46:49], v[134:137]
	v_mfma_i32_16x16x64_i8 v[134:137], v[26:29], v[82:85], v[158:161]
	v_mfma_i32_16x16x64_i8 v[158:161], v[30:33], v[86:89], v[134:137]
	v_mfma_i32_16x16x64_i8 v[134:137], v[34:37], v[82:85], v[154:157]
	v_mfma_i32_16x16x64_i8 v[154:157], v[38:41], v[86:89], v[134:137]
	v_mfma_i32_16x16x64_i8 v[134:137], v[26:29], v[214:217], v[142:145]
	v_mfma_i32_16x16x64_i8 v[142:145], v[30:33], v[218:221], v[134:137]
	v_mfma_i32_16x16x64_i8 v[134:137], v[34:37], v[214:217], v[138:141]
	v_mfma_i32_16x16x64_i8 v[126:129], v[26:29], v[222:225], v[126:129]
	v_mfma_i32_16x16x64_i8 v[122:125], v[34:37], v[222:225], v[122:125]
	v_mfma_i32_16x16x64_i8 v[138:141], v[38:41], v[218:221], v[134:137]
	v_mfma_i32_16x16x64_i8 v[126:129], v[30:33], v[240:243], v[126:129]
	v_mfma_i32_16x16x64_i8 v[122:125], v[38:41], v[240:243], v[122:125]
	v_mfma_i32_16x16x64_i8 v[134:137], v[178:181], v[42:45], v[166:169]
	v_mfma_i32_16x16x64_i8 v[42:45], v[186:189], v[42:45], v[98:101]
	v_mfma_i32_16x16x64_i8 v[162:165], v[190:193], v[46:49], v[42:45]
	v_mfma_i32_16x16x64_i8 v[42:45], v[178:181], v[82:85], v[102:105]
	v_mfma_i32_16x16x64_i8 v[150:153], v[182:185], v[86:89], v[42:45]
	v_mfma_i32_16x16x64_i8 v[42:45], v[186:189], v[82:85], v[106:109]
	v_mfma_i32_16x16x64_i8 v[146:149], v[190:193], v[86:89], v[42:45]
	v_mfma_i32_16x16x64_i8 v[42:45], v[178:181], v[214:217], v[110:113]
	v_mfma_i32_16x16x64_i8 v[166:169], v[182:185], v[46:49], v[134:137]
	v_mfma_i32_16x16x64_i8 v[134:137], v[182:185], v[218:221], v[42:45]
	v_mfma_i32_16x16x64_i8 v[42:45], v[186:189], v[214:217], v[130:133]
	v_mfma_i32_16x16x64_i8 v[130:133], v[190:193], v[218:221], v[42:45]
	v_mfma_i32_16x16x64_i8 v[42:45], v[178:181], v[222:225], v[118:121]
	v_mfma_i32_16x16x64_i8 v[118:121], v[182:185], v[240:243], v[42:45]
	v_mfma_i32_16x16x64_i8 v[42:45], v[186:189], v[222:225], v[114:117]
	v_mfma_i32_16x16x64_i8 v[114:117], v[190:193], v[240:243], v[42:45]
	s_barrier
	s_add_i32 s8, s81, s41
	s_nop 3
	v_lshl_add_u64 v[42:43], v[226:227], 0, s[24:25]
	s_mov_b32 m0, s8
	ds_read_b128 v[82:85], v236 offset:49152
	ds_read_b128 v[98:101], v236 offset:50176
	ds_read_b128 v[102:105], v236 offset:51200
	ds_read_b128 v[106:109], v236 offset:52224
	ds_read_b128 v[110:113], v236 offset:53248
	ds_read_b128 v[214:217], v236 offset:54272
	ds_read_b128 v[218:221], v236 offset:55296
	ds_read_b128 v[222:225], v236 offset:56320
	global_load_lds_dwordx4 v[42:43], off
	s_add_i32 m0, s8, 0x2000
	s_add_u32 s6, s6, 0x80080
	v_lshl_add_u64 v[42:43], v[244:245], 0, s[24:25]
	s_addc_u32 s7, s7, 0
	s_add_i32 s8, s82, s41
	global_load_lds_dwordx4 v[42:43], off
	v_lshl_add_u64 v[42:43], s[6:7], 0, v[196:197]
	s_mov_b32 m0, s8
	s_nop 0
	global_load_lds_dwordx4 v[42:43], off
	v_lshl_add_u64 v[42:43], s[6:7], 0, v[198:199]
	s_add_i32 m0, s8, 0x2000
	s_nop 0
	global_load_lds_dwordx4 v[42:43], off
	v_lshl_add_u64 v[42:43], v[246:247], 0, s[24:25]
	s_mov_b32 m0, s63
	s_nop 0
	global_load_lds_dwordx4 v[42:43], off
	v_lshl_add_u64 v[42:43], v[248:249], 0, s[24:25]
	s_mov_b32 m0, s64
	s_nop 0
	global_load_lds_dwordx4 v[42:43], off
	s_waitcnt vmcnt(8)
	s_waitcnt lgkmcnt(0)
	s_barrier
	s_waitcnt lgkmcnt(0)
	v_mfma_i32_16x16x64_i8 v[42:45], v[26:29], v[82:85], v[94:97]
	v_mfma_i32_16x16x64_i8 v[94:97], v[30:33], v[98:101], v[42:45]
	v_mfma_i32_16x16x64_i8 v[42:45], v[34:37], v[82:85], v[90:93]
	v_mfma_i32_16x16x64_i8 v[90:93], v[38:41], v[98:101], v[42:45]
	v_mfma_i32_16x16x64_i8 v[42:45], v[26:29], v[102:105], v[78:81]
	v_mfma_i32_16x16x64_i8 v[78:81], v[30:33], v[106:109], v[42:45]
	v_mfma_i32_16x16x64_i8 v[42:45], v[34:37], v[102:105], v[74:77]
	v_mfma_i32_16x16x64_i8 v[74:77], v[38:41], v[106:109], v[42:45]
	v_mfma_i32_16x16x64_i8 v[42:45], v[26:29], v[110:113], v[62:65]
	v_mfma_i32_16x16x64_i8 v[2:5], v[26:29], v[218:221], v[2:5]
	v_mfma_i32_16x16x64_i8 v[62:65], v[30:33], v[214:217], v[42:45]
	v_mfma_i32_16x16x64_i8 v[42:45], v[34:37], v[110:113], v[58:61]
	v_mfma_i32_16x16x64_i8 v[46:49], v[30:33], v[222:225], v[2:5]
	v_mfma_i32_16x16x64_i8 v[2:5], v[34:37], v[218:221], v[6:9]
	v_mfma_i32_16x16x64_i8 v[58:61], v[38:41], v[214:217], v[42:45]
	v_mfma_i32_16x16x64_i8 v[42:45], v[38:41], v[222:225], v[2:5]
	v_mfma_i32_16x16x64_i8 v[2:5], v[178:181], v[82:85], v[10:13]
	v_mfma_i32_16x16x64_i8 v[86:89], v[182:185], v[98:101], v[2:5]
	v_mfma_i32_16x16x64_i8 v[2:5], v[186:189], v[82:85], v[14:17]
	v_mfma_i32_16x16x64_i8 v[82:85], v[190:193], v[98:101], v[2:5]
	v_mfma_i32_16x16x64_i8 v[2:5], v[178:181], v[102:105], v[70:73]
	v_mfma_i32_16x16x64_i8 v[70:73], v[182:185], v[106:109], v[2:5]
	v_mfma_i32_16x16x64_i8 v[2:5], v[186:189], v[102:105], v[66:69]
	v_mfma_i32_16x16x64_i8 v[66:69], v[190:193], v[106:109], v[2:5]
	v_mfma_i32_16x16x64_i8 v[2:5], v[178:181], v[110:113], v[54:57]
	v_mfma_i32_16x16x64_i8 v[54:57], v[182:185], v[214:217], v[2:5]
	v_mfma_i32_16x16x64_i8 v[2:5], v[186:189], v[110:113], v[50:53]
	v_mfma_i32_16x16x64_i8 v[50:53], v[190:193], v[214:217], v[2:5]
	v_mfma_i32_16x16x64_i8 v[2:5], v[178:181], v[218:221], v[18:21]
	v_mfma_i32_16x16x64_i8 v[38:41], v[182:185], v[222:225], v[2:5]
	v_mfma_i32_16x16x64_i8 v[2:5], v[186:189], v[218:221], v[22:25]
	v_mfma_i32_16x16x64_i8 v[34:37], v[190:193], v[222:225], v[2:5]
	s_barrier
	s_add_i32 s80, s80, 2
	s_add_u32 s4, s4, 0x100
	s_addc_u32 s5, s5, 0
	s_add_u32 s78, s78, 0x100
	s_addc_u32 s79, s79, 0
	s_cmp_gt_u32 s80, 29
	s_cbranch_scc0 .LBB0_304
	s_and_b64 vcc, exec, s[12:13]
	s_cbranch_vccz .LBB0_307
	s_barrier

.LBB0_1232:
	ds_read_b128 v[106:109], v197
	ds_read_b128 v[114:117], v197 offset:1024
	ds_read_b128 v[122:125], v197 offset:2048
	ds_read_b128 v[130:133], v197 offset:3072
	ds_read_b128 v[146:149], v201
	ds_read_b128 v[150:153], v201 offset:1024
	ds_read_b128 v[154:157], v201 offset:2048
	ds_read_b128 v[158:161], v201 offset:3072
	s_add_u32 s30, s28, 0xfff80080
	s_addc_u32 s31, s29, -1
	s_cmp_eq_u32 s70, 28
	s_cselect_b32 s35, s23, s31
	s_cselect_b32 s34, s66, s30
	s_cselect_b32 s31, s15, s69
	s_cselect_b32 s30, s67, s68
	v_lshl_add_u64 v[194:195], s[28:29], 0, v[174:175]
	s_add_i32 m0, s19, 0xc000
	ds_read_b128 v[162:165], v204
	ds_read_b128 v[182:185], v204 offset:1024
	ds_read_b128 v[186:189], v204 offset:2048
	ds_read_b128 v[206:209], v204 offset:3072
	ds_read_b128 v[210:213], v204 offset:4096
	ds_read_b128 v[214:217], v204 offset:5120
	ds_read_b128 v[218:221], v204 offset:6144
	ds_read_b128 v[222:225], v204 offset:7168
	global_load_lds_dwordx4 v[194:195], off
	v_lshl_add_u64 v[194:195], s[28:29], 0, v[176:177]
	s_add_i32 m0, s19, 0xe000
	s_nop 0
	global_load_lds_dwordx4 v[194:195], off
	s_waitcnt vmcnt(8)
	s_waitcnt lgkmcnt(0)
	s_barrier
	s_waitcnt lgkmcnt(0)
	v_mfma_i32_16x16x64_i8 v[142:145], v[106:109], v[162:165], v[142:145]
	v_mfma_i32_16x16x64_i8 v[138:141], v[122:125], v[162:165], v[138:141]
	v_mfma_i32_16x16x64_i8 v[118:121], v[106:109], v[186:189], v[118:121]
	v_mfma_i32_16x16x64_i8 v[110:113], v[122:125], v[186:189], v[110:113]
	v_mfma_i32_16x16x64_i8 v[94:97], v[106:109], v[210:213], v[94:97]
	v_mfma_i32_16x16x64_i8 v[90:93], v[122:125], v[210:213], v[90:93]
	v_mfma_i32_16x16x64_i8 v[78:81], v[106:109], v[218:221], v[78:81]
	v_mfma_i32_16x16x64_i8 v[74:77], v[122:125], v[218:221], v[74:77]
	v_mfma_i32_16x16x64_i8 v[142:145], v[114:117], v[182:185], v[142:145]
	v_mfma_i32_16x16x64_i8 v[138:141], v[130:133], v[182:185], v[138:141]
	v_mfma_i32_16x16x64_i8 v[118:121], v[114:117], v[206:209], v[118:121]
	v_mfma_i32_16x16x64_i8 v[110:113], v[130:133], v[206:209], v[110:113]
	v_mfma_i32_16x16x64_i8 v[94:97], v[114:117], v[214:217], v[94:97]
	v_mfma_i32_16x16x64_i8 v[90:93], v[130:133], v[214:217], v[90:93]
	v_mfma_i32_16x16x64_i8 v[78:81], v[114:117], v[222:225], v[78:81]
	v_mfma_i32_16x16x64_i8 v[74:77], v[130:133], v[222:225], v[74:77]
	v_mfma_i32_16x16x64_i8 v[134:137], v[146:149], v[162:165], v[134:137]
	v_mfma_i32_16x16x64_i8 v[126:129], v[154:157], v[162:165], v[126:129]
	v_mfma_i32_16x16x64_i8 v[102:105], v[146:149], v[186:189], v[102:105]
	v_mfma_i32_16x16x64_i8 v[98:101], v[154:157], v[186:189], v[98:101]
	v_mfma_i32_16x16x64_i8 v[86:89], v[146:149], v[210:213], v[86:89]
	v_mfma_i32_16x16x64_i8 v[82:85], v[154:157], v[210:213], v[82:85]
	v_mfma_i32_16x16x64_i8 v[70:73], v[146:149], v[218:221], v[70:73]
	v_mfma_i32_16x16x64_i8 v[66:69], v[154:157], v[218:221], v[66:69]
	v_mfma_i32_16x16x64_i8 v[134:137], v[150:153], v[182:185], v[134:137]
	v_mfma_i32_16x16x64_i8 v[126:129], v[158:161], v[182:185], v[126:129]
	v_mfma_i32_16x16x64_i8 v[102:105], v[150:153], v[206:209], v[102:105]
	v_mfma_i32_16x16x64_i8 v[98:101], v[158:161], v[206:209], v[98:101]
	v_mfma_i32_16x16x64_i8 v[86:89], v[150:153], v[214:217], v[86:89]
	v_mfma_i32_16x16x64_i8 v[82:85], v[158:161], v[214:217], v[82:85]
	v_mfma_i32_16x16x64_i8 v[70:73], v[150:153], v[222:225], v[70:73]
	v_mfma_i32_16x16x64_i8 v[66:69], v[158:161], v[222:225], v[66:69]
	s_barrier
	s_add_i32 s71, s63, s39
	v_lshl_add_u64 v[194:195], s[30:31], 0, v[168:169]
	s_mov_b32 m0, s71
	ds_read_b128 v[162:165], v204 offset:16384
	ds_read_b128 v[182:185], v204 offset:17408
	ds_read_b128 v[186:189], v204 offset:18432
	ds_read_b128 v[206:209], v204 offset:19456
	ds_read_b128 v[210:213], v204 offset:20480
	ds_read_b128 v[214:217], v204 offset:21504
	ds_read_b128 v[218:221], v204 offset:22528
	ds_read_b128 v[222:225], v204 offset:23552
	global_load_lds_dwordx4 v[194:195], off
	s_add_i32 m0, s71, 0x2000
	s_add_u32 s72, s30, 0x80000
	v_lshl_add_u64 v[198:199], s[30:31], 0, v[172:173]
	s_addc_u32 s73, s31, 0
	s_add_i32 s71, s64, s39
	global_load_lds_dwordx4 v[198:199], off
	v_lshl_add_u64 v[202:203], s[72:73], 0, v[168:169]
	s_mov_b32 m0, s71
	v_lshl_add_u64 v[226:227], s[34:35], 0, v[170:171]
	global_load_lds_dwordx4 v[202:203], off
	v_lshl_add_u64 v[202:203], s[72:73], 0, v[172:173]
	s_add_i32 m0, s71, 0x2000
	s_nop 0
	global_load_lds_dwordx4 v[202:203], off
	v_lshl_add_u64 v[202:203], s[34:35], 0, v[166:167]
	s_mov_b32 m0, s19
	s_nop 0
	global_load_lds_dwordx4 v[202:203], off
	s_mov_b32 m0, s40
	s_nop 0
	global_load_lds_dwordx4 v[226:227], off
	s_waitcnt vmcnt(8)
	s_waitcnt lgkmcnt(0)
	s_barrier
	s_waitcnt lgkmcnt(0)
	v_mfma_i32_16x16x64_i8 v[62:65], v[106:109], v[162:165], v[62:65]
	v_mfma_i32_16x16x64_i8 v[58:61], v[122:125], v[162:165], v[58:61]
	v_mfma_i32_16x16x64_i8 v[46:49], v[106:109], v[186:189], v[46:49]
	v_mfma_i32_16x16x64_i8 v[42:45], v[122:125], v[186:189], v[42:45]
	v_mfma_i32_16x16x64_i8 v[30:33], v[106:109], v[210:213], v[30:33]
	v_mfma_i32_16x16x64_i8 v[26:29], v[122:125], v[210:213], v[26:29]
	v_mfma_i32_16x16x64_i8 v[14:17], v[106:109], v[218:221], v[14:17]
	v_mfma_i32_16x16x64_i8 v[10:13], v[122:125], v[218:221], v[10:13]
	v_mfma_i32_16x16x64_i8 v[62:65], v[114:117], v[182:185], v[62:65]
	v_mfma_i32_16x16x64_i8 v[58:61], v[130:133], v[182:185], v[58:61]
	v_mfma_i32_16x16x64_i8 v[46:49], v[114:117], v[206:209], v[46:49]
	v_mfma_i32_16x16x64_i8 v[42:45], v[130:133], v[206:209], v[42:45]
	v_mfma_i32_16x16x64_i8 v[30:33], v[114:117], v[214:217], v[30:33]
	v_mfma_i32_16x16x64_i8 v[26:29], v[130:133], v[214:217], v[26:29]
	v_mfma_i32_16x16x64_i8 v[14:17], v[114:117], v[222:225], v[14:17]
	v_mfma_i32_16x16x64_i8 v[10:13], v[130:133], v[222:225], v[10:13]
	v_mfma_i32_16x16x64_i8 v[54:57], v[146:149], v[162:165], v[54:57]
	v_mfma_i32_16x16x64_i8 v[50:53], v[154:157], v[162:165], v[50:53]
	v_mfma_i32_16x16x64_i8 v[38:41], v[146:149], v[186:189], v[38:41]
	v_mfma_i32_16x16x64_i8 v[34:37], v[154:157], v[186:189], v[34:37]
	v_mfma_i32_16x16x64_i8 v[22:25], v[146:149], v[210:213], v[22:25]
	v_mfma_i32_16x16x64_i8 v[18:21], v[154:157], v[210:213], v[18:21]
	v_mfma_i32_16x16x64_i8 v[6:9], v[146:149], v[218:221], v[6:9]
	v_mfma_i32_16x16x64_i8 v[2:5], v[154:157], v[218:221], v[2:5]
	v_mfma_i32_16x16x64_i8 v[54:57], v[150:153], v[182:185], v[54:57]
	v_mfma_i32_16x16x64_i8 v[50:53], v[158:161], v[182:185], v[50:53]
	v_mfma_i32_16x16x64_i8 v[38:41], v[150:153], v[206:209], v[38:41]
	v_mfma_i32_16x16x64_i8 v[34:37], v[158:161], v[206:209], v[34:37]
	v_mfma_i32_16x16x64_i8 v[22:25], v[150:153], v[214:217], v[22:25]
	v_mfma_i32_16x16x64_i8 v[18:21], v[158:161], v[214:217], v[18:21]
	v_mfma_i32_16x16x64_i8 v[6:9], v[150:153], v[222:225], v[6:9]
	v_mfma_i32_16x16x64_i8 v[2:5], v[158:161], v[222:225], v[2:5]
	s_barrier
	s_add_i32 s71, 0, 0x18000
	s_add_i32 s72, 0, 0x1c000
	v_add_u32_e32 v130, s71, v193
	v_add_u32_e32 v158, s72, v193
	ds_read_b128 v[106:109], v130
	ds_read_b128 v[114:117], v130 offset:1024
	ds_read_b128 v[122:125], v130 offset:2048
	ds_read_b128 v[130:133], v130 offset:3072
	ds_read_b128 v[146:149], v158
	ds_read_b128 v[150:153], v158 offset:1024
	ds_read_b128 v[154:157], v158 offset:2048
	ds_read_b128 v[158:161], v158 offset:3072
	s_add_u32 s34, s34, 0x80000
	s_addc_u32 s35, s35, 0
	s_mov_b32 m0, s41
	v_lshl_add_u64 v[228:229], s[34:35], 0, v[166:167]
	ds_read_b128 v[162:165], v204 offset:32768
	ds_read_b128 v[182:185], v204 offset:33792
	ds_read_b128 v[186:189], v204 offset:34816
	ds_read_b128 v[206:209], v204 offset:35840
	ds_read_b128 v[210:213], v204 offset:36864
	ds_read_b128 v[214:217], v204 offset:37888
	ds_read_b128 v[218:221], v204 offset:38912
	ds_read_b128 v[222:225], v204 offset:39936
	global_load_lds_dwordx4 v[228:229], off
	v_lshl_add_u64 v[228:229], s[34:35], 0, v[170:171]
	s_mov_b32 m0, s42
	s_nop 0
	global_load_lds_dwordx4 v[228:229], off
	s_waitcnt vmcnt(8)
	s_waitcnt lgkmcnt(0)
	s_barrier
	s_waitcnt lgkmcnt(0)
	v_mfma_i32_16x16x64_i8 v[142:145], v[106:109], v[162:165], v[142:145]
	v_mfma_i32_16x16x64_i8 v[138:141], v[122:125], v[162:165], v[138:141]
	v_mfma_i32_16x16x64_i8 v[118:121], v[106:109], v[186:189], v[118:121]
	v_mfma_i32_16x16x64_i8 v[110:113], v[122:125], v[186:189], v[110:113]
	v_mfma_i32_16x16x64_i8 v[94:97], v[106:109], v[210:213], v[94:97]
	v_mfma_i32_16x16x64_i8 v[90:93], v[122:125], v[210:213], v[90:93]
	v_mfma_i32_16x16x64_i8 v[78:81], v[106:109], v[218:221], v[78:81]
	v_mfma_i32_16x16x64_i8 v[74:77], v[122:125], v[218:221], v[74:77]
	v_mfma_i32_16x16x64_i8 v[142:145], v[114:117], v[182:185], v[142:145]
	v_mfma_i32_16x16x64_i8 v[138:141], v[130:133], v[182:185], v[138:141]
	v_mfma_i32_16x16x64_i8 v[118:121], v[114:117], v[206:209], v[118:121]
	v_mfma_i32_16x16x64_i8 v[110:113], v[130:133], v[206:209], v[110:113]
	v_mfma_i32_16x16x64_i8 v[94:97], v[114:117], v[214:217], v[94:97]
	v_mfma_i32_16x16x64_i8 v[90:93], v[130:133], v[214:217], v[90:93]
	v_mfma_i32_16x16x64_i8 v[78:81], v[114:117], v[222:225], v[78:81]
	v_mfma_i32_16x16x64_i8 v[74:77], v[130:133], v[222:225], v[74:77]
	v_mfma_i32_16x16x64_i8 v[134:137], v[146:149], v[162:165], v[134:137]
	v_mfma_i32_16x16x64_i8 v[126:129], v[154:157], v[162:165], v[126:129]
	v_mfma_i32_16x16x64_i8 v[102:105], v[146:149], v[186:189], v[102:105]
	v_mfma_i32_16x16x64_i8 v[98:101], v[154:157], v[186:189], v[98:101]
	v_mfma_i32_16x16x64_i8 v[86:89], v[146:149], v[210:213], v[86:89]
	v_mfma_i32_16x16x64_i8 v[82:85], v[154:157], v[210:213], v[82:85]
	v_mfma_i32_16x16x64_i8 v[70:73], v[146:149], v[218:221], v[70:73]
	v_mfma_i32_16x16x64_i8 v[66:69], v[154:157], v[218:221], v[66:69]
	v_mfma_i32_16x16x64_i8 v[134:137], v[150:153], v[182:185], v[134:137]
	v_mfma_i32_16x16x64_i8 v[126:129], v[158:161], v[182:185], v[126:129]
	v_mfma_i32_16x16x64_i8 v[102:105], v[150:153], v[206:209], v[102:105]
	v_mfma_i32_16x16x64_i8 v[98:101], v[158:161], v[206:209], v[98:101]
	v_mfma_i32_16x16x64_i8 v[86:89], v[150:153], v[214:217], v[86:89]
	v_mfma_i32_16x16x64_i8 v[82:85], v[158:161], v[214:217], v[82:85]
	v_mfma_i32_16x16x64_i8 v[70:73], v[150:153], v[222:225], v[70:73]
	v_mfma_i32_16x16x64_i8 v[66:69], v[158:161], v[222:225], v[66:69]
	s_barrier
	s_add_i32 s34, s71, s39
	v_lshl_add_u64 v[194:195], v[194:195], 0, s[10:11]
	s_mov_b32 m0, s34
	ds_read_b128 v[162:165], v204 offset:49152
	ds_read_b128 v[182:185], v204 offset:50176
	ds_read_b128 v[186:189], v204 offset:51200
	ds_read_b128 v[206:209], v204 offset:52224
	ds_read_b128 v[210:213], v204 offset:53248
	ds_read_b128 v[214:217], v204 offset:54272
	ds_read_b128 v[218:221], v204 offset:55296
	ds_read_b128 v[222:225], v204 offset:56320
	global_load_lds_dwordx4 v[194:195], off
	s_add_i32 m0, s34, 0x2000
	s_add_u32 s30, s30, 0x80080
	v_lshl_add_u64 v[194:195], v[198:199], 0, s[10:11]
	s_addc_u32 s31, s31, 0
	s_add_i32 s34, s72, s39
	global_load_lds_dwordx4 v[194:195], off
	v_lshl_add_u64 v[194:195], s[30:31], 0, v[168:169]
	s_mov_b32 m0, s34
	s_nop 0
	global_load_lds_dwordx4 v[194:195], off
	v_lshl_add_u64 v[194:195], s[30:31], 0, v[172:173]
	s_add_i32 m0, s34, 0x2000
	s_nop 0
	global_load_lds_dwordx4 v[194:195], off
	v_lshl_add_u64 v[194:195], v[202:203], 0, s[10:11]
	s_mov_b32 m0, s60
	s_nop 0
	global_load_lds_dwordx4 v[194:195], off
	v_lshl_add_u64 v[194:195], v[226:227], 0, s[10:11]
	s_mov_b32 m0, s61
	s_nop 0
	global_load_lds_dwordx4 v[194:195], off
	s_waitcnt vmcnt(8)
	s_waitcnt lgkmcnt(0)
	s_barrier
	s_waitcnt lgkmcnt(0)
	v_mfma_i32_16x16x64_i8 v[62:65], v[106:109], v[162:165], v[62:65]
	v_mfma_i32_16x16x64_i8 v[58:61], v[122:125], v[162:165], v[58:61]
	v_mfma_i32_16x16x64_i8 v[46:49], v[106:109], v[186:189], v[46:49]
	v_mfma_i32_16x16x64_i8 v[42:45], v[122:125], v[186:189], v[42:45]
	v_mfma_i32_16x16x64_i8 v[30:33], v[106:109], v[210:213], v[30:33]
	v_mfma_i32_16x16x64_i8 v[26:29], v[122:125], v[210:213], v[26:29]
	v_mfma_i32_16x16x64_i8 v[14:17], v[106:109], v[218:221], v[14:17]
	v_mfma_i32_16x16x64_i8 v[10:13], v[122:125], v[218:221], v[10:13]
	v_mfma_i32_16x16x64_i8 v[62:65], v[114:117], v[182:185], v[62:65]
	v_mfma_i32_16x16x64_i8 v[58:61], v[130:133], v[182:185], v[58:61]
	v_mfma_i32_16x16x64_i8 v[46:49], v[114:117], v[206:209], v[46:49]
	v_mfma_i32_16x16x64_i8 v[42:45], v[130:133], v[206:209], v[42:45]
	v_mfma_i32_16x16x64_i8 v[30:33], v[114:117], v[214:217], v[30:33]
	v_mfma_i32_16x16x64_i8 v[26:29], v[130:133], v[214:217], v[26:29]
	v_mfma_i32_16x16x64_i8 v[14:17], v[114:117], v[222:225], v[14:17]
	v_mfma_i32_16x16x64_i8 v[10:13], v[130:133], v[222:225], v[10:13]
	v_mfma_i32_16x16x64_i8 v[54:57], v[146:149], v[162:165], v[54:57]
	v_mfma_i32_16x16x64_i8 v[50:53], v[154:157], v[162:165], v[50:53]
	v_mfma_i32_16x16x64_i8 v[38:41], v[146:149], v[186:189], v[38:41]
	v_mfma_i32_16x16x64_i8 v[34:37], v[154:157], v[186:189], v[34:37]
	v_mfma_i32_16x16x64_i8 v[22:25], v[146:149], v[210:213], v[22:25]
	v_mfma_i32_16x16x64_i8 v[18:21], v[154:157], v[210:213], v[18:21]
	v_mfma_i32_16x16x64_i8 v[6:9], v[146:149], v[218:221], v[6:9]
	v_mfma_i32_16x16x64_i8 v[2:5], v[154:157], v[218:221], v[2:5]
	v_mfma_i32_16x16x64_i8 v[54:57], v[150:153], v[182:185], v[54:57]
	v_mfma_i32_16x16x64_i8 v[50:53], v[158:161], v[182:185], v[50:53]
	v_mfma_i32_16x16x64_i8 v[38:41], v[150:153], v[206:209], v[38:41]
	v_mfma_i32_16x16x64_i8 v[34:37], v[158:161], v[206:209], v[34:37]
	v_mfma_i32_16x16x64_i8 v[22:25], v[150:153], v[214:217], v[22:25]
	v_mfma_i32_16x16x64_i8 v[18:21], v[158:161], v[214:217], v[18:21]
	v_mfma_i32_16x16x64_i8 v[6:9], v[150:153], v[222:225], v[6:9]
	v_mfma_i32_16x16x64_i8 v[2:5], v[158:161], v[222:225], v[2:5]
	s_barrier
	s_add_i32 s70, s70, 2
	s_add_u32 s28, s28, 0x100
	s_addc_u32 s29, s29, 0
	s_add_u32 s68, s68, 0x100
	s_addc_u32 s69, s69, 0
	s_cmp_gt_u32 s70, 29
	s_cbranch_scc0 .LBB0_1232
	s_and_b64 vcc, exec, s[12:13]
	s_cbranch_vccz .LBB0_1235
	s_barrier

.LBB0_1367:
	ds_read_b128 v[130:133], v234
	ds_read_b128 v[134:137], v234 offset:1024
	ds_read_b128 v[162:165], v234 offset:2048
	ds_read_b128 v[166:169], v234 offset:3072
	ds_read_b128 v[170:173], v235
	ds_read_b128 v[174:177], v235 offset:1024
	ds_read_b128 v[178:181], v235 offset:2048
	ds_read_b128 v[182:185], v235 offset:3072
	s_add_u32 s6, s4, 0x100
	s_addc_u32 s7, s5, 0
	s_cmp_eq_u32 s80, 28
	s_cselect_b32 s57, s35, s7
	s_cselect_b32 s56, s43, s6
	s_cselect_b32 s19, s31, s79
	s_cselect_b32 s18, vcc_lo, vcc_hi
	v_lshl_add_u64 v[218:219], s[4:5], 0, v[154:155]
	s_add_i32 m0, s65, 0xc000
	ds_read_b128 v[186:189], v236
	ds_read_b128 v[190:193], v236 offset:1024
	ds_read_b128 v[194:197], v236 offset:2048
	ds_read_b128 v[198:201], v236 offset:3072
	ds_read_b128 v[202:205], v236 offset:4096
	ds_read_b128 v[206:209], v236 offset:5120
	ds_read_b128 v[210:213], v236 offset:6144
	ds_read_b128 v[214:217], v236 offset:7168
	global_load_lds_dwordx4 v[218:219], off
	v_lshl_add_u64 v[218:219], s[4:5], 0, v[156:157]
	s_add_i32 m0, s65, 0xe000
	s_nop 0
	global_load_lds_dwordx4 v[218:219], off
	s_waitcnt vmcnt(8)
	s_waitcnt lgkmcnt(0)
	s_barrier
	s_waitcnt lgkmcnt(0)
	v_mfma_i32_16x16x64_i8 v[118:121], v[130:133], v[186:189], v[118:121]
	v_mfma_i32_16x16x64_i8 v[102:105], v[162:165], v[186:189], v[102:105]
	v_mfma_i32_16x16x64_i8 v[114:117], v[130:133], v[194:197], v[114:117]
	v_mfma_i32_16x16x64_i8 v[98:101], v[162:165], v[194:197], v[98:101]
	v_mfma_i32_16x16x64_i8 v[126:129], v[130:133], v[202:205], v[126:129]
	v_mfma_i32_16x16x64_i8 v[110:113], v[162:165], v[202:205], v[110:113]
	v_mfma_i32_16x16x64_i8 v[122:125], v[130:133], v[210:213], v[122:125]
	v_mfma_i32_16x16x64_i8 v[106:109], v[162:165], v[210:213], v[106:109]
	v_mfma_i32_16x16x64_i8 v[118:121], v[134:137], v[190:193], v[118:121]
	v_mfma_i32_16x16x64_i8 v[102:105], v[166:169], v[190:193], v[102:105]
	v_mfma_i32_16x16x64_i8 v[114:117], v[134:137], v[198:201], v[114:117]
	v_mfma_i32_16x16x64_i8 v[98:101], v[166:169], v[198:201], v[98:101]
	v_mfma_i32_16x16x64_i8 v[126:129], v[134:137], v[206:209], v[126:129]
	v_mfma_i32_16x16x64_i8 v[110:113], v[166:169], v[206:209], v[110:113]
	v_mfma_i32_16x16x64_i8 v[122:125], v[134:137], v[214:217], v[122:125]
	v_mfma_i32_16x16x64_i8 v[106:109], v[166:169], v[214:217], v[106:109]
	v_mfma_i32_16x16x64_i8 v[86:89], v[170:173], v[186:189], v[86:89]
	v_mfma_i32_16x16x64_i8 v[70:73], v[178:181], v[186:189], v[70:73]
	v_mfma_i32_16x16x64_i8 v[82:85], v[170:173], v[194:197], v[82:85]
	v_mfma_i32_16x16x64_i8 v[66:69], v[178:181], v[194:197], v[66:69]
	v_mfma_i32_16x16x64_i8 v[94:97], v[170:173], v[202:205], v[94:97]
	v_mfma_i32_16x16x64_i8 v[78:81], v[178:181], v[202:205], v[78:81]
	v_mfma_i32_16x16x64_i8 v[90:93], v[170:173], v[210:213], v[90:93]
	v_mfma_i32_16x16x64_i8 v[74:77], v[178:181], v[210:213], v[74:77]
	v_mfma_i32_16x16x64_i8 v[86:89], v[174:177], v[190:193], v[86:89]
	v_mfma_i32_16x16x64_i8 v[70:73], v[182:185], v[190:193], v[70:73]
	v_mfma_i32_16x16x64_i8 v[82:85], v[174:177], v[198:201], v[82:85]
	v_mfma_i32_16x16x64_i8 v[66:69], v[182:185], v[198:201], v[66:69]
	v_mfma_i32_16x16x64_i8 v[94:97], v[174:177], v[206:209], v[94:97]
	v_mfma_i32_16x16x64_i8 v[78:81], v[182:185], v[206:209], v[78:81]
	v_mfma_i32_16x16x64_i8 v[90:93], v[174:177], v[214:217], v[90:93]
	v_mfma_i32_16x16x64_i8 v[74:77], v[182:185], v[214:217], v[74:77]
	s_barrier
	s_add_i32 s4, s97, s63
	v_lshl_add_u64 v[218:219], s[18:19], 0, v[144:145]
	s_mov_b32 m0, s4
	ds_read_b128 v[186:189], v236 offset:16384
	ds_read_b128 v[190:193], v236 offset:17408
	ds_read_b128 v[194:197], v236 offset:18432
	ds_read_b128 v[198:201], v236 offset:19456
	ds_read_b128 v[202:205], v236 offset:20480
	ds_read_b128 v[206:209], v236 offset:21504
	ds_read_b128 v[210:213], v236 offset:22528
	ds_read_b128 v[214:217], v236 offset:23552
	global_load_lds_dwordx4 v[218:219], off
	s_add_i32 m0, s4, 0x2000
	s_add_u32 s4, s18, 0x80000
	v_lshl_add_u64 v[220:221], s[18:19], 0, v[148:149]
	s_addc_u32 s5, s19, 0
	s_add_i32 s81, s0, s63
	global_load_lds_dwordx4 v[220:221], off
	v_lshl_add_u64 v[222:223], s[4:5], 0, v[144:145]
	s_mov_b32 m0, s81
	v_lshl_add_u64 v[224:225], s[56:57], 0, v[146:147]
	global_load_lds_dwordx4 v[222:223], off
	v_lshl_add_u64 v[222:223], s[4:5], 0, v[148:149]
	s_add_i32 m0, s81, 0x2000
	s_nop 0
	global_load_lds_dwordx4 v[222:223], off
	v_lshl_add_u64 v[222:223], s[56:57], 0, v[142:143]
	s_mov_b32 m0, s65
	s_nop 0
	global_load_lds_dwordx4 v[222:223], off
	s_mov_b32 m0, s66
	s_nop 0
	global_load_lds_dwordx4 v[224:225], off
	s_waitcnt vmcnt(8)
	s_waitcnt lgkmcnt(0)
	s_barrier
	s_waitcnt lgkmcnt(0)
	v_mfma_i32_16x16x64_i8 v[54:57], v[130:133], v[186:189], v[54:57]
	v_mfma_i32_16x16x64_i8 v[18:21], v[162:165], v[186:189], v[18:21]
	v_mfma_i32_16x16x64_i8 v[50:53], v[130:133], v[194:197], v[50:53]
	v_mfma_i32_16x16x64_i8 v[22:25], v[162:165], v[194:197], v[22:25]
	v_mfma_i32_16x16x64_i8 v[62:65], v[130:133], v[202:205], v[62:65]
	v_mfma_i32_16x16x64_i8 v[30:33], v[162:165], v[202:205], v[30:33]
	v_mfma_i32_16x16x64_i8 v[58:61], v[130:133], v[210:213], v[58:61]
	v_mfma_i32_16x16x64_i8 v[26:29], v[162:165], v[210:213], v[26:29]
	v_mfma_i32_16x16x64_i8 v[54:57], v[134:137], v[190:193], v[54:57]
	v_mfma_i32_16x16x64_i8 v[18:21], v[166:169], v[190:193], v[18:21]
	v_mfma_i32_16x16x64_i8 v[50:53], v[134:137], v[198:201], v[50:53]
	v_mfma_i32_16x16x64_i8 v[22:25], v[166:169], v[198:201], v[22:25]
	v_mfma_i32_16x16x64_i8 v[62:65], v[134:137], v[206:209], v[62:65]
	v_mfma_i32_16x16x64_i8 v[30:33], v[166:169], v[206:209], v[30:33]
	v_mfma_i32_16x16x64_i8 v[58:61], v[134:137], v[214:217], v[58:61]
	v_mfma_i32_16x16x64_i8 v[26:29], v[166:169], v[214:217], v[26:29]
	v_mfma_i32_16x16x64_i8 v[46:49], v[170:173], v[186:189], v[46:49]
	v_mfma_i32_16x16x64_i8 v[14:17], v[178:181], v[186:189], v[14:17]
	v_mfma_i32_16x16x64_i8 v[42:45], v[170:173], v[194:197], v[42:45]
	v_mfma_i32_16x16x64_i8 v[10:13], v[178:181], v[194:197], v[10:13]
	v_mfma_i32_16x16x64_i8 v[38:41], v[170:173], v[202:205], v[38:41]
	v_mfma_i32_16x16x64_i8 v[6:9], v[178:181], v[202:205], v[6:9]
	v_mfma_i32_16x16x64_i8 v[34:37], v[170:173], v[210:213], v[34:37]
	v_mfma_i32_16x16x64_i8 v[2:5], v[178:181], v[210:213], v[2:5]
	v_mfma_i32_16x16x64_i8 v[46:49], v[174:177], v[190:193], v[46:49]
	v_mfma_i32_16x16x64_i8 v[14:17], v[182:185], v[190:193], v[14:17]
	v_mfma_i32_16x16x64_i8 v[42:45], v[174:177], v[198:201], v[42:45]
	v_mfma_i32_16x16x64_i8 v[10:13], v[182:185], v[198:201], v[10:13]
	v_mfma_i32_16x16x64_i8 v[38:41], v[174:177], v[206:209], v[38:41]
	v_mfma_i32_16x16x64_i8 v[6:9], v[182:185], v[206:209], v[6:9]
	v_mfma_i32_16x16x64_i8 v[34:37], v[174:177], v[214:217], v[34:37]
	v_mfma_i32_16x16x64_i8 v[2:5], v[182:185], v[214:217], v[2:5]
	s_barrier
	s_add_i32 s81, 0, 0x18000
	s_add_i32 s82, 0, 0x1c000
	v_add_u32_e32 v166, s81, v232
	v_add_u32_e32 v182, s82, v232
	ds_read_b128 v[130:133], v166
	ds_read_b128 v[134:137], v166 offset:1024
	ds_read_b128 v[162:165], v166 offset:2048
	ds_read_b128 v[166:169], v166 offset:3072
	ds_read_b128 v[170:173], v182
	ds_read_b128 v[174:177], v182 offset:1024
	ds_read_b128 v[178:181], v182 offset:2048
	ds_read_b128 v[182:185], v182 offset:3072
	s_add_u32 s4, s56, 0x80000
	s_addc_u32 s5, s57, 0
	s_mov_b32 m0, s67
	v_lshl_add_u64 v[226:227], s[4:5], 0, v[142:143]
	ds_read_b128 v[186:189], v236 offset:32768
	ds_read_b128 v[190:193], v236 offset:33792
	ds_read_b128 v[194:197], v236 offset:34816
	ds_read_b128 v[198:201], v236 offset:35840
	ds_read_b128 v[202:205], v236 offset:36864
	ds_read_b128 v[206:209], v236 offset:37888
	ds_read_b128 v[210:213], v236 offset:38912
	ds_read_b128 v[214:217], v236 offset:39936
	global_load_lds_dwordx4 v[226:227], off
	v_lshl_add_u64 v[226:227], s[4:5], 0, v[146:147]
	s_mov_b32 m0, s68
	s_nop 0
	global_load_lds_dwordx4 v[226:227], off
	s_waitcnt vmcnt(8)
	s_waitcnt lgkmcnt(0)
	s_barrier
	s_waitcnt lgkmcnt(0)
	v_mfma_i32_16x16x64_i8 v[118:121], v[130:133], v[186:189], v[118:121]
	v_mfma_i32_16x16x64_i8 v[102:105], v[162:165], v[186:189], v[102:105]
	v_mfma_i32_16x16x64_i8 v[114:117], v[130:133], v[194:197], v[114:117]
	v_mfma_i32_16x16x64_i8 v[98:101], v[162:165], v[194:197], v[98:101]
	v_mfma_i32_16x16x64_i8 v[126:129], v[130:133], v[202:205], v[126:129]
	v_mfma_i32_16x16x64_i8 v[110:113], v[162:165], v[202:205], v[110:113]
	v_mfma_i32_16x16x64_i8 v[122:125], v[130:133], v[210:213], v[122:125]
	v_mfma_i32_16x16x64_i8 v[106:109], v[162:165], v[210:213], v[106:109]
	v_mfma_i32_16x16x64_i8 v[118:121], v[134:137], v[190:193], v[118:121]
	v_mfma_i32_16x16x64_i8 v[102:105], v[166:169], v[190:193], v[102:105]
	v_mfma_i32_16x16x64_i8 v[114:117], v[134:137], v[198:201], v[114:117]
	v_mfma_i32_16x16x64_i8 v[98:101], v[166:169], v[198:201], v[98:101]
	v_mfma_i32_16x16x64_i8 v[126:129], v[134:137], v[206:209], v[126:129]
	v_mfma_i32_16x16x64_i8 v[110:113], v[166:169], v[206:209], v[110:113]
	v_mfma_i32_16x16x64_i8 v[122:125], v[134:137], v[214:217], v[122:125]
	v_mfma_i32_16x16x64_i8 v[106:109], v[166:169], v[214:217], v[106:109]
	v_mfma_i32_16x16x64_i8 v[86:89], v[170:173], v[186:189], v[86:89]
	v_mfma_i32_16x16x64_i8 v[70:73], v[178:181], v[186:189], v[70:73]
	v_mfma_i32_16x16x64_i8 v[82:85], v[170:173], v[194:197], v[82:85]
	v_mfma_i32_16x16x64_i8 v[66:69], v[178:181], v[194:197], v[66:69]
	v_mfma_i32_16x16x64_i8 v[94:97], v[170:173], v[202:205], v[94:97]
	v_mfma_i32_16x16x64_i8 v[78:81], v[178:181], v[202:205], v[78:81]
	v_mfma_i32_16x16x64_i8 v[90:93], v[170:173], v[210:213], v[90:93]
	v_mfma_i32_16x16x64_i8 v[74:77], v[178:181], v[210:213], v[74:77]
	v_mfma_i32_16x16x64_i8 v[86:89], v[174:177], v[190:193], v[86:89]
	v_mfma_i32_16x16x64_i8 v[70:73], v[182:185], v[190:193], v[70:73]
	v_mfma_i32_16x16x64_i8 v[82:85], v[174:177], v[198:201], v[82:85]
	v_mfma_i32_16x16x64_i8 v[66:69], v[182:185], v[198:201], v[66:69]
	v_mfma_i32_16x16x64_i8 v[94:97], v[174:177], v[206:209], v[94:97]
	v_mfma_i32_16x16x64_i8 v[78:81], v[182:185], v[206:209], v[78:81]
	v_mfma_i32_16x16x64_i8 v[90:93], v[174:177], v[214:217], v[90:93]
	v_mfma_i32_16x16x64_i8 v[74:77], v[182:185], v[214:217], v[74:77]
	s_barrier
	s_add_i32 s4, s81, s63
	v_lshl_add_u64 v[218:219], v[218:219], 0, s[22:23]
	s_mov_b32 m0, s4
	ds_read_b128 v[186:189], v236 offset:49152
	ds_read_b128 v[190:193], v236 offset:50176
	ds_read_b128 v[194:197], v236 offset:51200
	ds_read_b128 v[198:201], v236 offset:52224
	ds_read_b128 v[202:205], v236 offset:53248
	ds_read_b128 v[206:209], v236 offset:54272
	ds_read_b128 v[210:213], v236 offset:55296
	ds_read_b128 v[214:217], v236 offset:56320
	global_load_lds_dwordx4 v[218:219], off
	s_add_i32 m0, s4, 0x2000
	s_add_u32 s4, s18, 0x80080
	v_lshl_add_u64 v[218:219], v[220:221], 0, s[22:23]
	s_addc_u32 s5, s19, 0
	s_add_i32 s18, s82, s63
	global_load_lds_dwordx4 v[218:219], off
	v_lshl_add_u64 v[218:219], s[4:5], 0, v[144:145]
	s_mov_b32 m0, s18
	s_nop 0
	global_load_lds_dwordx4 v[218:219], off
	v_lshl_add_u64 v[218:219], s[4:5], 0, v[148:149]
	s_add_i32 m0, s18, 0x2000
	s_nop 0
	global_load_lds_dwordx4 v[218:219], off
	v_lshl_add_u64 v[218:219], v[222:223], 0, s[22:23]
	s_mov_b32 m0, s77
	s_nop 0
	global_load_lds_dwordx4 v[218:219], off
	v_lshl_add_u64 v[218:219], v[224:225], 0, s[22:23]
	s_mov_b32 m0, s78
	s_nop 0
	global_load_lds_dwordx4 v[218:219], off
	s_waitcnt vmcnt(8)
	s_waitcnt lgkmcnt(0)
	s_barrier
	s_waitcnt lgkmcnt(0)
	v_mfma_i32_16x16x64_i8 v[54:57], v[130:133], v[186:189], v[54:57]
	v_mfma_i32_16x16x64_i8 v[18:21], v[162:165], v[186:189], v[18:21]
	v_mfma_i32_16x16x64_i8 v[50:53], v[130:133], v[194:197], v[50:53]
	v_mfma_i32_16x16x64_i8 v[22:25], v[162:165], v[194:197], v[22:25]
	v_mfma_i32_16x16x64_i8 v[62:65], v[130:133], v[202:205], v[62:65]
	v_mfma_i32_16x16x64_i8 v[30:33], v[162:165], v[202:205], v[30:33]
	v_mfma_i32_16x16x64_i8 v[58:61], v[130:133], v[210:213], v[58:61]
	v_mfma_i32_16x16x64_i8 v[26:29], v[162:165], v[210:213], v[26:29]
	v_mfma_i32_16x16x64_i8 v[54:57], v[134:137], v[190:193], v[54:57]
	v_mfma_i32_16x16x64_i8 v[18:21], v[166:169], v[190:193], v[18:21]
	v_mfma_i32_16x16x64_i8 v[50:53], v[134:137], v[198:201], v[50:53]
	v_mfma_i32_16x16x64_i8 v[22:25], v[166:169], v[198:201], v[22:25]
	v_mfma_i32_16x16x64_i8 v[62:65], v[134:137], v[206:209], v[62:65]
	v_mfma_i32_16x16x64_i8 v[30:33], v[166:169], v[206:209], v[30:33]
	v_mfma_i32_16x16x64_i8 v[58:61], v[134:137], v[214:217], v[58:61]
	v_mfma_i32_16x16x64_i8 v[26:29], v[166:169], v[214:217], v[26:29]
	v_mfma_i32_16x16x64_i8 v[46:49], v[170:173], v[186:189], v[46:49]
	v_mfma_i32_16x16x64_i8 v[14:17], v[178:181], v[186:189], v[14:17]
	v_mfma_i32_16x16x64_i8 v[42:45], v[170:173], v[194:197], v[42:45]
	v_mfma_i32_16x16x64_i8 v[10:13], v[178:181], v[194:197], v[10:13]
	v_mfma_i32_16x16x64_i8 v[38:41], v[170:173], v[202:205], v[38:41]
	v_mfma_i32_16x16x64_i8 v[6:9], v[178:181], v[202:205], v[6:9]
	v_mfma_i32_16x16x64_i8 v[34:37], v[170:173], v[210:213], v[34:37]
	v_mfma_i32_16x16x64_i8 v[2:5], v[178:181], v[210:213], v[2:5]
	v_mfma_i32_16x16x64_i8 v[46:49], v[174:177], v[190:193], v[46:49]
	v_mfma_i32_16x16x64_i8 v[14:17], v[182:185], v[190:193], v[14:17]
	v_mfma_i32_16x16x64_i8 v[42:45], v[174:177], v[198:201], v[42:45]
	v_mfma_i32_16x16x64_i8 v[10:13], v[182:185], v[198:201], v[10:13]
	v_mfma_i32_16x16x64_i8 v[38:41], v[174:177], v[206:209], v[38:41]
	v_mfma_i32_16x16x64_i8 v[6:9], v[182:185], v[206:209], v[6:9]
	v_mfma_i32_16x16x64_i8 v[34:37], v[174:177], v[214:217], v[34:37]
	v_mfma_i32_16x16x64_i8 v[2:5], v[182:185], v[214:217], v[2:5]
	s_barrier
	s_add_i32 s80, s80, 2
	s_add_u32 vcc_hi, vcc_hi, 0x100
	s_addc_u32 s79, s79, 0
	s_cmp_gt_u32 s80, 29
	s_mov_b64 s[4:5], s[6:7]
	s_cbranch_scc0 .LBB0_1367
	s_and_b64 vcc, exec, s[10:11]
	s_cbranch_vccz .LBB0_1370
	s_barrier

.LBB0_1554:
	ds_read_b128 v[114:117], v247
	ds_read_b128 v[118:121], v247 offset:1024
	ds_read_b128 v[126:129], v247 offset:2048
	ds_read_b128 v[134:137], v247 offset:3072
	ds_read_b128 v[138:141], v248
	ds_read_b128 v[142:145], v248 offset:1024
	ds_read_b128 v[154:157], v248 offset:2048
	ds_read_b128 v[158:161], v248 offset:3072
	s_add_u32 s4, s18, 0x100
	s_addc_u32 s5, s19, 0
	s_cmpk_eq_i32 s66, 0xdc
	s_cselect_b32 s29, s23, s5
	s_cselect_b32 s28, s22, s4
	s_cselect_b32 s27, s25, s65
	s_cselect_b32 s26, s24, s64
	v_lshl_add_u64 v[210:211], s[18:19], 0, v[202:203]
	s_add_i32 m0, s17, 0xc000
	ds_read_b128 v[162:165], v249
	ds_read_b128 v[166:169], v249 offset:1024
	ds_read_b128 v[170:173], v249 offset:2048
	ds_read_b128 v[174:177], v249 offset:3072
	ds_read_b128 v[178:181], v249 offset:4096
	ds_read_b128 v[182:185], v249 offset:5120
	ds_read_b128 v[186:189], v249 offset:6144
	ds_read_b128 v[190:193], v249 offset:7168
	global_load_lds_dwordx4 v[210:211], off
	v_lshl_add_u64 v[210:211], s[18:19], 0, v[204:205]
	s_add_i32 m0, s17, 0xe000
	s_nop 0
	global_load_lds_dwordx4 v[210:211], off
	s_waitcnt vmcnt(8)
	s_waitcnt lgkmcnt(0)
	s_barrier
	s_waitcnt lgkmcnt(0)
	v_mfma_f32_16x16x32_bf16 v[150:153], v[114:117], v[162:165], v[150:153]
	v_mfma_f32_16x16x32_bf16 v[146:149], v[126:129], v[162:165], v[146:149]
	v_mfma_f32_16x16x32_bf16 v[110:113], v[114:117], v[170:173], v[110:113]
	v_mfma_f32_16x16x32_bf16 v[106:109], v[126:129], v[170:173], v[106:109]
	v_mfma_f32_16x16x32_bf16 v[94:97], v[114:117], v[178:181], v[94:97]
	v_mfma_f32_16x16x32_bf16 v[90:93], v[126:129], v[178:181], v[90:93]
	v_mfma_f32_16x16x32_bf16 v[78:81], v[114:117], v[186:189], v[78:81]
	v_mfma_f32_16x16x32_bf16 v[74:77], v[126:129], v[186:189], v[74:77]
	v_mfma_f32_16x16x32_bf16 v[150:153], v[118:121], v[166:169], v[150:153]
	v_mfma_f32_16x16x32_bf16 v[146:149], v[134:137], v[166:169], v[146:149]
	v_mfma_f32_16x16x32_bf16 v[110:113], v[118:121], v[174:177], v[110:113]
	v_mfma_f32_16x16x32_bf16 v[106:109], v[134:137], v[174:177], v[106:109]
	v_mfma_f32_16x16x32_bf16 v[94:97], v[118:121], v[182:185], v[94:97]
	v_mfma_f32_16x16x32_bf16 v[90:93], v[134:137], v[182:185], v[90:93]
	v_mfma_f32_16x16x32_bf16 v[78:81], v[118:121], v[190:193], v[78:81]
	v_mfma_f32_16x16x32_bf16 v[74:77], v[134:137], v[190:193], v[74:77]
	v_mfma_f32_16x16x32_bf16 v[130:133], v[138:141], v[162:165], v[130:133]
	v_mfma_f32_16x16x32_bf16 v[122:125], v[154:157], v[162:165], v[122:125]
	v_mfma_f32_16x16x32_bf16 v[102:105], v[138:141], v[170:173], v[102:105]
	v_mfma_f32_16x16x32_bf16 v[98:101], v[154:157], v[170:173], v[98:101]
	v_mfma_f32_16x16x32_bf16 v[86:89], v[138:141], v[178:181], v[86:89]
	v_mfma_f32_16x16x32_bf16 v[82:85], v[154:157], v[178:181], v[82:85]
	v_mfma_f32_16x16x32_bf16 v[70:73], v[138:141], v[186:189], v[70:73]
	v_mfma_f32_16x16x32_bf16 v[66:69], v[154:157], v[186:189], v[66:69]
	v_mfma_f32_16x16x32_bf16 v[130:133], v[142:145], v[166:169], v[130:133]
	v_mfma_f32_16x16x32_bf16 v[122:125], v[158:161], v[166:169], v[122:125]
	v_mfma_f32_16x16x32_bf16 v[102:105], v[142:145], v[174:177], v[102:105]
	v_mfma_f32_16x16x32_bf16 v[98:101], v[158:161], v[174:177], v[98:101]
	v_mfma_f32_16x16x32_bf16 v[86:89], v[142:145], v[182:185], v[86:89]
	v_mfma_f32_16x16x32_bf16 v[82:85], v[158:161], v[182:185], v[82:85]
	v_mfma_f32_16x16x32_bf16 v[70:73], v[142:145], v[190:193], v[70:73]
	v_mfma_f32_16x16x32_bf16 v[66:69], v[158:161], v[190:193], v[66:69]
	s_barrier
	s_add_i32 s18, s42, s16
	v_lshl_add_u64 v[210:211], s[26:27], 0, v[196:197]
	s_mov_b32 m0, s18
	ds_read_b128 v[162:165], v249 offset:16384
	ds_read_b128 v[166:169], v249 offset:17408
	ds_read_b128 v[170:173], v249 offset:18432
	ds_read_b128 v[174:177], v249 offset:19456
	ds_read_b128 v[178:181], v249 offset:20480
	ds_read_b128 v[182:185], v249 offset:21504
	ds_read_b128 v[186:189], v249 offset:22528
	ds_read_b128 v[190:193], v249 offset:23552
	global_load_lds_dwordx4 v[210:211], off
	s_add_i32 m0, s18, 0x2000
	s_add_u32 s18, s26, 0x380000
	v_lshl_add_u64 v[212:213], s[26:27], 0, v[200:201]
	s_addc_u32 s19, s27, 0
	s_add_i32 s67, s43, s16
	global_load_lds_dwordx4 v[212:213], off
	v_lshl_add_u64 v[214:215], s[18:19], 0, v[196:197]
	s_mov_b32 m0, s67
	v_lshl_add_u64 v[216:217], s[28:29], 0, v[198:199]
	global_load_lds_dwordx4 v[214:215], off
	v_lshl_add_u64 v[214:215], s[18:19], 0, v[200:201]
	s_add_i32 m0, s67, 0x2000
	s_nop 0
	global_load_lds_dwordx4 v[214:215], off
	v_lshl_add_u64 v[214:215], s[28:29], 0, v[194:195]
	s_mov_b32 m0, s17
	s_nop 0
	global_load_lds_dwordx4 v[214:215], off
	s_mov_b32 m0, s30
	s_nop 0
	global_load_lds_dwordx4 v[216:217], off
	s_waitcnt vmcnt(8)
	s_waitcnt lgkmcnt(0)
	s_barrier
	s_waitcnt lgkmcnt(0)
	v_mfma_f32_16x16x32_bf16 v[62:65], v[114:117], v[162:165], v[62:65]
	v_mfma_f32_16x16x32_bf16 v[58:61], v[126:129], v[162:165], v[58:61]
	v_mfma_f32_16x16x32_bf16 v[46:49], v[114:117], v[170:173], v[46:49]
	v_mfma_f32_16x16x32_bf16 v[42:45], v[126:129], v[170:173], v[42:45]
	v_mfma_f32_16x16x32_bf16 v[30:33], v[114:117], v[178:181], v[30:33]
	v_mfma_f32_16x16x32_bf16 v[26:29], v[126:129], v[178:181], v[26:29]
	v_mfma_f32_16x16x32_bf16 v[14:17], v[114:117], v[186:189], v[14:17]
	v_mfma_f32_16x16x32_bf16 v[10:13], v[126:129], v[186:189], v[10:13]
	v_mfma_f32_16x16x32_bf16 v[62:65], v[118:121], v[166:169], v[62:65]
	v_mfma_f32_16x16x32_bf16 v[58:61], v[134:137], v[166:169], v[58:61]
	v_mfma_f32_16x16x32_bf16 v[46:49], v[118:121], v[174:177], v[46:49]
	v_mfma_f32_16x16x32_bf16 v[42:45], v[134:137], v[174:177], v[42:45]
	v_mfma_f32_16x16x32_bf16 v[30:33], v[118:121], v[182:185], v[30:33]
	v_mfma_f32_16x16x32_bf16 v[26:29], v[134:137], v[182:185], v[26:29]
	v_mfma_f32_16x16x32_bf16 v[14:17], v[118:121], v[190:193], v[14:17]
	v_mfma_f32_16x16x32_bf16 v[10:13], v[134:137], v[190:193], v[10:13]
	v_mfma_f32_16x16x32_bf16 v[54:57], v[138:141], v[162:165], v[54:57]
	v_mfma_f32_16x16x32_bf16 v[50:53], v[154:157], v[162:165], v[50:53]
	v_mfma_f32_16x16x32_bf16 v[38:41], v[138:141], v[170:173], v[38:41]
	v_mfma_f32_16x16x32_bf16 v[34:37], v[154:157], v[170:173], v[34:37]
	v_mfma_f32_16x16x32_bf16 v[22:25], v[138:141], v[178:181], v[22:25]
	v_mfma_f32_16x16x32_bf16 v[18:21], v[154:157], v[178:181], v[18:21]
	v_mfma_f32_16x16x32_bf16 v[6:9], v[138:141], v[186:189], v[6:9]
	v_mfma_f32_16x16x32_bf16 v[2:5], v[154:157], v[186:189], v[2:5]
	v_mfma_f32_16x16x32_bf16 v[54:57], v[142:145], v[166:169], v[54:57]
	v_mfma_f32_16x16x32_bf16 v[50:53], v[158:161], v[166:169], v[50:53]
	v_mfma_f32_16x16x32_bf16 v[38:41], v[142:145], v[174:177], v[38:41]
	v_mfma_f32_16x16x32_bf16 v[34:37], v[158:161], v[174:177], v[34:37]
	v_mfma_f32_16x16x32_bf16 v[22:25], v[142:145], v[182:185], v[22:25]
	v_mfma_f32_16x16x32_bf16 v[18:21], v[158:161], v[182:185], v[18:21]
	v_mfma_f32_16x16x32_bf16 v[6:9], v[142:145], v[190:193], v[6:9]
	v_mfma_f32_16x16x32_bf16 v[2:5], v[158:161], v[190:193], v[2:5]
	s_barrier
	s_add_i32 s67, 0, 0x18000
	s_add_i32 s68, 0, 0x1c000
	v_add_u32_e32 v134, s67, v244
	v_add_u32_e32 v158, s68, v244
	ds_read_b128 v[114:117], v134
	ds_read_b128 v[118:121], v134 offset:1024
	ds_read_b128 v[126:129], v134 offset:2048
	ds_read_b128 v[134:137], v134 offset:3072
	ds_read_b128 v[138:141], v158
	ds_read_b128 v[142:145], v158 offset:1024
	ds_read_b128 v[154:157], v158 offset:2048
	ds_read_b128 v[158:161], v158 offset:3072
	s_add_u32 s18, s28, 0x380000
	s_addc_u32 s19, s29, 0
	s_mov_b32 m0, s31
	v_lshl_add_u64 v[218:219], s[18:19], 0, v[194:195]
	ds_read_b128 v[162:165], v249 offset:32768
	ds_read_b128 v[166:169], v249 offset:33792
	ds_read_b128 v[170:173], v249 offset:34816
	ds_read_b128 v[174:177], v249 offset:35840
	ds_read_b128 v[178:181], v249 offset:36864
	ds_read_b128 v[182:185], v249 offset:37888
	ds_read_b128 v[186:189], v249 offset:38912
	ds_read_b128 v[190:193], v249 offset:39936
	global_load_lds_dwordx4 v[218:219], off
	v_lshl_add_u64 v[218:219], s[18:19], 0, v[198:199]
	s_mov_b32 m0, s34
	s_nop 0
	global_load_lds_dwordx4 v[218:219], off
	s_waitcnt vmcnt(8)
	s_waitcnt lgkmcnt(0)
	s_barrier
	s_waitcnt lgkmcnt(0)
	v_mfma_f32_16x16x32_bf16 v[150:153], v[114:117], v[162:165], v[150:153]
	v_mfma_f32_16x16x32_bf16 v[146:149], v[126:129], v[162:165], v[146:149]
	v_mfma_f32_16x16x32_bf16 v[110:113], v[114:117], v[170:173], v[110:113]
	v_mfma_f32_16x16x32_bf16 v[106:109], v[126:129], v[170:173], v[106:109]
	v_mfma_f32_16x16x32_bf16 v[94:97], v[114:117], v[178:181], v[94:97]
	v_mfma_f32_16x16x32_bf16 v[90:93], v[126:129], v[178:181], v[90:93]
	v_mfma_f32_16x16x32_bf16 v[78:81], v[114:117], v[186:189], v[78:81]
	v_mfma_f32_16x16x32_bf16 v[74:77], v[126:129], v[186:189], v[74:77]
	v_mfma_f32_16x16x32_bf16 v[150:153], v[118:121], v[166:169], v[150:153]
	v_mfma_f32_16x16x32_bf16 v[146:149], v[134:137], v[166:169], v[146:149]
	v_mfma_f32_16x16x32_bf16 v[110:113], v[118:121], v[174:177], v[110:113]
	v_mfma_f32_16x16x32_bf16 v[106:109], v[134:137], v[174:177], v[106:109]
	v_mfma_f32_16x16x32_bf16 v[94:97], v[118:121], v[182:185], v[94:97]
	v_mfma_f32_16x16x32_bf16 v[90:93], v[134:137], v[182:185], v[90:93]
	v_mfma_f32_16x16x32_bf16 v[78:81], v[118:121], v[190:193], v[78:81]
	v_mfma_f32_16x16x32_bf16 v[74:77], v[134:137], v[190:193], v[74:77]
	v_mfma_f32_16x16x32_bf16 v[130:133], v[138:141], v[162:165], v[130:133]
	v_mfma_f32_16x16x32_bf16 v[122:125], v[154:157], v[162:165], v[122:125]
	v_mfma_f32_16x16x32_bf16 v[102:105], v[138:141], v[170:173], v[102:105]
	v_mfma_f32_16x16x32_bf16 v[98:101], v[154:157], v[170:173], v[98:101]
	v_mfma_f32_16x16x32_bf16 v[86:89], v[138:141], v[178:181], v[86:89]
	v_mfma_f32_16x16x32_bf16 v[82:85], v[154:157], v[178:181], v[82:85]
	v_mfma_f32_16x16x32_bf16 v[70:73], v[138:141], v[186:189], v[70:73]
	v_mfma_f32_16x16x32_bf16 v[66:69], v[154:157], v[186:189], v[66:69]
	v_mfma_f32_16x16x32_bf16 v[130:133], v[142:145], v[166:169], v[130:133]
	v_mfma_f32_16x16x32_bf16 v[122:125], v[158:161], v[166:169], v[122:125]
	v_mfma_f32_16x16x32_bf16 v[102:105], v[142:145], v[174:177], v[102:105]
	v_mfma_f32_16x16x32_bf16 v[98:101], v[158:161], v[174:177], v[98:101]
	v_mfma_f32_16x16x32_bf16 v[86:89], v[142:145], v[182:185], v[86:89]
	v_mfma_f32_16x16x32_bf16 v[82:85], v[158:161], v[182:185], v[82:85]
	v_mfma_f32_16x16x32_bf16 v[70:73], v[142:145], v[190:193], v[70:73]
	v_mfma_f32_16x16x32_bf16 v[66:69], v[158:161], v[190:193], v[66:69]
	s_barrier
	s_add_i32 s18, s67, s16
	v_lshl_add_u64 v[210:211], v[210:211], 0, s[12:13]
	s_mov_b32 m0, s18
	ds_read_b128 v[162:165], v249 offset:49152
	ds_read_b128 v[166:169], v249 offset:50176
	ds_read_b128 v[170:173], v249 offset:51200
	ds_read_b128 v[174:177], v249 offset:52224
	ds_read_b128 v[178:181], v249 offset:53248
	ds_read_b128 v[182:185], v249 offset:54272
	ds_read_b128 v[186:189], v249 offset:55296
	ds_read_b128 v[190:193], v249 offset:56320
	global_load_lds_dwordx4 v[210:211], off
	s_add_i32 m0, s18, 0x2000
	s_add_u32 s18, s26, 0x380080
	v_lshl_add_u64 v[210:211], v[212:213], 0, s[12:13]
	s_addc_u32 s19, s27, 0
	s_add_i32 s26, s68, s16
	global_load_lds_dwordx4 v[210:211], off
	v_lshl_add_u64 v[210:211], s[18:19], 0, v[196:197]
	s_mov_b32 m0, s26
	s_nop 0
	global_load_lds_dwordx4 v[210:211], off
	v_lshl_add_u64 v[210:211], s[18:19], 0, v[200:201]
	s_add_i32 m0, s26, 0x2000
	s_nop 0
	global_load_lds_dwordx4 v[210:211], off
	v_lshl_add_u64 v[210:211], v[214:215], 0, s[12:13]
	s_mov_b32 m0, s38
	s_nop 0
	global_load_lds_dwordx4 v[210:211], off
	v_lshl_add_u64 v[210:211], v[216:217], 0, s[12:13]
	s_mov_b32 m0, s39
	s_nop 0
	global_load_lds_dwordx4 v[210:211], off
	s_waitcnt vmcnt(8)
	s_waitcnt lgkmcnt(0)
	s_barrier
	s_waitcnt lgkmcnt(0)
	v_mfma_f32_16x16x32_bf16 v[62:65], v[114:117], v[162:165], v[62:65]
	v_mfma_f32_16x16x32_bf16 v[58:61], v[126:129], v[162:165], v[58:61]
	v_mfma_f32_16x16x32_bf16 v[46:49], v[114:117], v[170:173], v[46:49]
	v_mfma_f32_16x16x32_bf16 v[42:45], v[126:129], v[170:173], v[42:45]
	v_mfma_f32_16x16x32_bf16 v[30:33], v[114:117], v[178:181], v[30:33]
	v_mfma_f32_16x16x32_bf16 v[26:29], v[126:129], v[178:181], v[26:29]
	v_mfma_f32_16x16x32_bf16 v[14:17], v[114:117], v[186:189], v[14:17]
	v_mfma_f32_16x16x32_bf16 v[10:13], v[126:129], v[186:189], v[10:13]
	v_mfma_f32_16x16x32_bf16 v[62:65], v[118:121], v[166:169], v[62:65]
	v_mfma_f32_16x16x32_bf16 v[58:61], v[134:137], v[166:169], v[58:61]
	v_mfma_f32_16x16x32_bf16 v[46:49], v[118:121], v[174:177], v[46:49]
	v_mfma_f32_16x16x32_bf16 v[42:45], v[134:137], v[174:177], v[42:45]
	v_mfma_f32_16x16x32_bf16 v[30:33], v[118:121], v[182:185], v[30:33]
	v_mfma_f32_16x16x32_bf16 v[26:29], v[134:137], v[182:185], v[26:29]
	v_mfma_f32_16x16x32_bf16 v[14:17], v[118:121], v[190:193], v[14:17]
	v_mfma_f32_16x16x32_bf16 v[10:13], v[134:137], v[190:193], v[10:13]
	v_mfma_f32_16x16x32_bf16 v[54:57], v[138:141], v[162:165], v[54:57]
	v_mfma_f32_16x16x32_bf16 v[50:53], v[154:157], v[162:165], v[50:53]
	v_mfma_f32_16x16x32_bf16 v[38:41], v[138:141], v[170:173], v[38:41]
	v_mfma_f32_16x16x32_bf16 v[34:37], v[154:157], v[170:173], v[34:37]
	v_mfma_f32_16x16x32_bf16 v[22:25], v[138:141], v[178:181], v[22:25]
	v_mfma_f32_16x16x32_bf16 v[18:21], v[154:157], v[178:181], v[18:21]
	v_mfma_f32_16x16x32_bf16 v[6:9], v[138:141], v[186:189], v[6:9]
	v_mfma_f32_16x16x32_bf16 v[2:5], v[154:157], v[186:189], v[2:5]
	v_mfma_f32_16x16x32_bf16 v[54:57], v[142:145], v[166:169], v[54:57]
	v_mfma_f32_16x16x32_bf16 v[50:53], v[158:161], v[166:169], v[50:53]
	v_mfma_f32_16x16x32_bf16 v[38:41], v[142:145], v[174:177], v[38:41]
	v_mfma_f32_16x16x32_bf16 v[34:37], v[158:161], v[174:177], v[34:37]
	v_mfma_f32_16x16x32_bf16 v[22:25], v[142:145], v[182:185], v[22:25]
	v_mfma_f32_16x16x32_bf16 v[18:21], v[158:161], v[182:185], v[18:21]
	v_mfma_f32_16x16x32_bf16 v[6:9], v[142:145], v[190:193], v[6:9]
	v_mfma_f32_16x16x32_bf16 v[2:5], v[158:161], v[190:193], v[2:5]
	s_barrier
	s_add_i32 s66, s66, 2
	s_add_u32 s64, s64, 0x100
	s_addc_u32 s65, s65, 0
	s_cmpk_gt_u32 s66, 0xdd
	s_mov_b64 s[18:19], s[4:5]
	s_cbranch_scc0 .LBB0_1554
	s_and_b64 vcc, exec, s[14:15]
	s_cbranch_vccz .LBB0_1557
	s_barrier

.LBB0_1647:
	ds_read_b128 v[30:33], v200
	ds_read_b128 v[38:41], v200 offset:1024
	ds_read_b128 v[42:45], v200 offset:2048
	ds_read_b128 v[50:53], v200 offset:3072
	ds_read_b128 v[164:167], v201
	ds_read_b128 v[168:171], v201 offset:1024
	ds_read_b128 v[172:175], v201 offset:2048
	ds_read_b128 v[176:179], v201 offset:3072
	s_add_u32 s18, s10, 0xfff00080
	s_addc_u32 s19, s11, -1
	s_cmp_eq_u32 s61, 60
	s_cselect_b32 s69, s0, s19
	s_cselect_b32 s68, s1, s18
	s_cselect_b32 s19, s7, s17
	s_cselect_b32 s18, s9, s16
	v_lshl_add_u64 v[222:223], s[10:11], 0, v[156:157]
	s_add_i32 m0, s39, 0xc000
	ds_read_b128 v[180:183], v202
	ds_read_b128 v[184:187], v202 offset:1024
	ds_read_b128 v[188:191], v202 offset:2048
	ds_read_b128 v[192:195], v202 offset:3072
	ds_read_b128 v[206:209], v202 offset:4096
	ds_read_b128 v[210:213], v202 offset:5120
	ds_read_b128 v[214:217], v202 offset:6144
	ds_read_b128 v[218:221], v202 offset:7168
	global_load_lds_dwordx4 v[222:223], off
	v_lshl_add_u64 v[222:223], s[10:11], 0, v[158:159]
	s_add_i32 m0, s39, 0xe000
	s_nop 0
	global_load_lds_dwordx4 v[222:223], off
	s_waitcnt vmcnt(8)
	s_waitcnt lgkmcnt(0)
	s_barrier
	s_waitcnt lgkmcnt(0)
	v_mfma_f32_16x16x32_bf16 v[138:141], v[30:33], v[180:183], v[138:141]
	v_mfma_f32_16x16x32_bf16 v[142:145], v[42:45], v[180:183], v[142:145]
	v_mfma_f32_16x16x32_bf16 v[122:125], v[30:33], v[188:191], v[122:125]
	v_mfma_f32_16x16x32_bf16 v[126:129], v[42:45], v[188:191], v[126:129]
	v_mfma_f32_16x16x32_bf16 v[106:109], v[30:33], v[206:209], v[106:109]
	v_mfma_f32_16x16x32_bf16 v[110:113], v[42:45], v[206:209], v[110:113]
	v_mfma_f32_16x16x32_bf16 v[90:93], v[30:33], v[214:217], v[90:93]
	v_mfma_f32_16x16x32_bf16 v[94:97], v[42:45], v[214:217], v[94:97]
	v_mfma_f32_16x16x32_bf16 v[138:141], v[38:41], v[184:187], v[138:141]
	v_mfma_f32_16x16x32_bf16 v[142:145], v[50:53], v[184:187], v[142:145]
	v_mfma_f32_16x16x32_bf16 v[122:125], v[38:41], v[192:195], v[122:125]
	v_mfma_f32_16x16x32_bf16 v[126:129], v[50:53], v[192:195], v[126:129]
	v_mfma_f32_16x16x32_bf16 v[106:109], v[38:41], v[210:213], v[106:109]
	v_mfma_f32_16x16x32_bf16 v[110:113], v[50:53], v[210:213], v[110:113]
	v_mfma_f32_16x16x32_bf16 v[90:93], v[38:41], v[218:221], v[90:93]
	v_mfma_f32_16x16x32_bf16 v[94:97], v[50:53], v[218:221], v[94:97]
	v_mfma_f32_16x16x32_bf16 v[130:133], v[164:167], v[180:183], v[130:133]
	v_mfma_f32_16x16x32_bf16 v[134:137], v[172:175], v[180:183], v[134:137]
	v_mfma_f32_16x16x32_bf16 v[114:117], v[164:167], v[188:191], v[114:117]
	v_mfma_f32_16x16x32_bf16 v[118:121], v[172:175], v[188:191], v[118:121]
	v_mfma_f32_16x16x32_bf16 v[98:101], v[164:167], v[206:209], v[98:101]
	v_mfma_f32_16x16x32_bf16 v[102:105], v[172:175], v[206:209], v[102:105]
	v_mfma_f32_16x16x32_bf16 v[82:85], v[164:167], v[214:217], v[82:85]
	v_mfma_f32_16x16x32_bf16 v[86:89], v[172:175], v[214:217], v[86:89]
	v_mfma_f32_16x16x32_bf16 v[130:133], v[168:171], v[184:187], v[130:133]
	v_mfma_f32_16x16x32_bf16 v[134:137], v[176:179], v[184:187], v[134:137]
	v_mfma_f32_16x16x32_bf16 v[114:117], v[168:171], v[192:195], v[114:117]
	v_mfma_f32_16x16x32_bf16 v[118:121], v[176:179], v[192:195], v[118:121]
	v_mfma_f32_16x16x32_bf16 v[98:101], v[168:171], v[210:213], v[98:101]
	v_mfma_f32_16x16x32_bf16 v[102:105], v[176:179], v[210:213], v[102:105]
	v_mfma_f32_16x16x32_bf16 v[82:85], v[168:171], v[218:221], v[82:85]
	v_mfma_f32_16x16x32_bf16 v[86:89], v[176:179], v[218:221], v[86:89]
	s_barrier
	s_add_i32 s63, s77, s37
	v_lshl_add_u64 v[222:223], s[18:19], 0, v[148:149]
	s_mov_b32 m0, s63
	ds_read_b128 v[180:183], v202 offset:16384
	ds_read_b128 v[184:187], v202 offset:17408
	ds_read_b128 v[188:191], v202 offset:18432
	ds_read_b128 v[192:195], v202 offset:19456
	ds_read_b128 v[206:209], v202 offset:20480
	ds_read_b128 v[210:213], v202 offset:21504
	ds_read_b128 v[214:217], v202 offset:22528
	ds_read_b128 v[218:221], v202 offset:23552
	global_load_lds_dwordx4 v[222:223], off
	s_add_i32 m0, s63, 0x2000
	s_add_u32 s82, s18, 0x100000
	v_lshl_add_u64 v[224:225], s[18:19], 0, v[152:153]
	s_addc_u32 s83, s19, 0
	s_add_i32 s63, s78, s37
	global_load_lds_dwordx4 v[224:225], off
	v_lshl_add_u64 v[226:227], s[82:83], 0, v[148:149]
	s_mov_b32 m0, s63
	v_lshl_add_u64 v[228:229], s[68:69], 0, v[150:151]
	global_load_lds_dwordx4 v[226:227], off
	v_lshl_add_u64 v[226:227], s[82:83], 0, v[152:153]
	s_add_i32 m0, s63, 0x2000
	s_nop 0
	global_load_lds_dwordx4 v[226:227], off
	v_lshl_add_u64 v[226:227], s[68:69], 0, v[146:147]
	s_mov_b32 m0, s39
	s_nop 0
	global_load_lds_dwordx4 v[226:227], off
	s_mov_b32 m0, s41
	s_nop 0
	global_load_lds_dwordx4 v[228:229], off
	s_waitcnt vmcnt(8)
	s_waitcnt lgkmcnt(0)
	s_barrier
	s_waitcnt lgkmcnt(0)
	v_mfma_f32_16x16x32_bf16 v[74:77], v[30:33], v[180:183], v[74:77]
	v_mfma_f32_16x16x32_bf16 v[78:81], v[42:45], v[180:183], v[78:81]
	v_mfma_f32_16x16x32_bf16 v[58:61], v[30:33], v[188:191], v[58:61]
	v_mfma_f32_16x16x32_bf16 v[62:65], v[42:45], v[188:191], v[62:65]
	v_mfma_f32_16x16x32_bf16 v[26:29], v[30:33], v[206:209], v[26:29]
	v_mfma_f32_16x16x32_bf16 v[34:37], v[42:45], v[206:209], v[34:37]
	v_mfma_f32_16x16x32_bf16 v[10:13], v[30:33], v[214:217], v[10:13]
	v_mfma_f32_16x16x32_bf16 v[14:17], v[42:45], v[214:217], v[14:17]
	v_mfma_f32_16x16x32_bf16 v[74:77], v[38:41], v[184:187], v[74:77]
	v_mfma_f32_16x16x32_bf16 v[78:81], v[50:53], v[184:187], v[78:81]
	v_mfma_f32_16x16x32_bf16 v[58:61], v[38:41], v[192:195], v[58:61]
	v_mfma_f32_16x16x32_bf16 v[62:65], v[50:53], v[192:195], v[62:65]
	v_mfma_f32_16x16x32_bf16 v[26:29], v[38:41], v[210:213], v[26:29]
	v_mfma_f32_16x16x32_bf16 v[34:37], v[50:53], v[210:213], v[34:37]
	v_mfma_f32_16x16x32_bf16 v[10:13], v[38:41], v[218:221], v[10:13]
	v_mfma_f32_16x16x32_bf16 v[14:17], v[50:53], v[218:221], v[14:17]
	v_mfma_f32_16x16x32_bf16 v[18:21], v[164:167], v[206:209], v[18:21]
	v_mfma_f32_16x16x32_bf16 v[22:25], v[172:175], v[206:209], v[22:25]
	v_mfma_f32_16x16x32_bf16 v[2:5], v[164:167], v[214:217], v[2:5]
	v_mfma_f32_16x16x32_bf16 v[6:9], v[172:175], v[214:217], v[6:9]
	v_mfma_f32_16x16x32_bf16 v[30:33], v[164:167], v[180:183], v[66:69]
	v_mfma_f32_16x16x32_bf16 v[38:41], v[172:175], v[180:183], v[70:73]
	v_mfma_f32_16x16x32_bf16 v[42:45], v[164:167], v[188:191], v[46:49]
	v_mfma_f32_16x16x32_bf16 v[46:49], v[172:175], v[188:191], v[54:57]
	v_mfma_f32_16x16x32_bf16 v[18:21], v[168:171], v[210:213], v[18:21]
	v_mfma_f32_16x16x32_bf16 v[22:25], v[176:179], v[210:213], v[22:25]
	v_mfma_f32_16x16x32_bf16 v[2:5], v[168:171], v[218:221], v[2:5]
	v_mfma_f32_16x16x32_bf16 v[6:9], v[176:179], v[218:221], v[6:9]
	v_mfma_f32_16x16x32_bf16 v[30:33], v[168:171], v[184:187], v[30:33]
	v_mfma_f32_16x16x32_bf16 v[38:41], v[176:179], v[184:187], v[38:41]
	v_mfma_f32_16x16x32_bf16 v[42:45], v[168:171], v[192:195], v[42:45]
	v_mfma_f32_16x16x32_bf16 v[50:53], v[176:179], v[192:195], v[46:49]
	s_barrier
	s_add_i32 s63, 0, 0x18000
	s_add_i32 s82, 0, 0x1c000
	v_add_u32_e32 v70, s63, v196
	v_add_u32_e32 v155, s82, v196
	ds_read_b128 v[46:49], v70
	ds_read_b128 v[54:57], v70 offset:1024
	ds_read_b128 v[66:69], v70 offset:2048
	ds_read_b128 v[70:73], v70 offset:3072
	ds_read_b128 v[164:167], v155
	ds_read_b128 v[168:171], v155 offset:1024
	ds_read_b128 v[172:175], v155 offset:2048
	ds_read_b128 v[176:179], v155 offset:3072
	s_add_u32 s68, s68, 0x100000
	s_addc_u32 s69, s69, 0
	s_mov_b32 m0, s43
	v_lshl_add_u64 v[230:231], s[68:69], 0, v[146:147]
	ds_read_b128 v[180:183], v202 offset:32768
	ds_read_b128 v[184:187], v202 offset:33792
	ds_read_b128 v[188:191], v202 offset:34816
	ds_read_b128 v[192:195], v202 offset:35840
	ds_read_b128 v[206:209], v202 offset:36864
	ds_read_b128 v[210:213], v202 offset:37888
	ds_read_b128 v[214:217], v202 offset:38912
	ds_read_b128 v[218:221], v202 offset:39936
	global_load_lds_dwordx4 v[230:231], off
	v_lshl_add_u64 v[230:231], s[68:69], 0, v[150:151]
	s_mov_b32 m0, s57
	s_nop 0
	global_load_lds_dwordx4 v[230:231], off
	s_waitcnt vmcnt(8)
	s_waitcnt lgkmcnt(0)
	s_barrier
	s_waitcnt lgkmcnt(0)
	v_mfma_f32_16x16x32_bf16 v[138:141], v[46:49], v[180:183], v[138:141]
	v_mfma_f32_16x16x32_bf16 v[142:145], v[66:69], v[180:183], v[142:145]
	v_mfma_f32_16x16x32_bf16 v[122:125], v[46:49], v[188:191], v[122:125]
	v_mfma_f32_16x16x32_bf16 v[126:129], v[66:69], v[188:191], v[126:129]
	v_mfma_f32_16x16x32_bf16 v[106:109], v[46:49], v[206:209], v[106:109]
	v_mfma_f32_16x16x32_bf16 v[110:113], v[66:69], v[206:209], v[110:113]
	v_mfma_f32_16x16x32_bf16 v[90:93], v[46:49], v[214:217], v[90:93]
	v_mfma_f32_16x16x32_bf16 v[94:97], v[66:69], v[214:217], v[94:97]
	v_mfma_f32_16x16x32_bf16 v[138:141], v[54:57], v[184:187], v[138:141]
	v_mfma_f32_16x16x32_bf16 v[142:145], v[70:73], v[184:187], v[142:145]
	v_mfma_f32_16x16x32_bf16 v[122:125], v[54:57], v[192:195], v[122:125]
	v_mfma_f32_16x16x32_bf16 v[126:129], v[70:73], v[192:195], v[126:129]
	v_mfma_f32_16x16x32_bf16 v[106:109], v[54:57], v[210:213], v[106:109]
	v_mfma_f32_16x16x32_bf16 v[110:113], v[70:73], v[210:213], v[110:113]
	v_mfma_f32_16x16x32_bf16 v[90:93], v[54:57], v[218:221], v[90:93]
	v_mfma_f32_16x16x32_bf16 v[94:97], v[70:73], v[218:221], v[94:97]
	v_mfma_f32_16x16x32_bf16 v[130:133], v[164:167], v[180:183], v[130:133]
	v_mfma_f32_16x16x32_bf16 v[134:137], v[172:175], v[180:183], v[134:137]
	v_mfma_f32_16x16x32_bf16 v[114:117], v[164:167], v[188:191], v[114:117]
	v_mfma_f32_16x16x32_bf16 v[118:121], v[172:175], v[188:191], v[118:121]
	v_mfma_f32_16x16x32_bf16 v[98:101], v[164:167], v[206:209], v[98:101]
	v_mfma_f32_16x16x32_bf16 v[102:105], v[172:175], v[206:209], v[102:105]
	v_mfma_f32_16x16x32_bf16 v[82:85], v[164:167], v[214:217], v[82:85]
	v_mfma_f32_16x16x32_bf16 v[86:89], v[172:175], v[214:217], v[86:89]
	v_mfma_f32_16x16x32_bf16 v[130:133], v[168:171], v[184:187], v[130:133]
	v_mfma_f32_16x16x32_bf16 v[134:137], v[176:179], v[184:187], v[134:137]
	v_mfma_f32_16x16x32_bf16 v[114:117], v[168:171], v[192:195], v[114:117]
	v_mfma_f32_16x16x32_bf16 v[118:121], v[176:179], v[192:195], v[118:121]
	v_mfma_f32_16x16x32_bf16 v[98:101], v[168:171], v[210:213], v[98:101]
	v_mfma_f32_16x16x32_bf16 v[102:105], v[176:179], v[210:213], v[102:105]
	v_mfma_f32_16x16x32_bf16 v[82:85], v[168:171], v[218:221], v[82:85]
	v_mfma_f32_16x16x32_bf16 v[86:89], v[176:179], v[218:221], v[86:89]
	s_barrier
	s_add_i32 s63, s63, s37
	v_lshl_add_u64 v[222:223], v[222:223], 0, s[26:27]
	s_mov_b32 m0, s63
	ds_read_b128 v[180:183], v202 offset:49152
	ds_read_b128 v[184:187], v202 offset:50176
	ds_read_b128 v[188:191], v202 offset:51200
	ds_read_b128 v[192:195], v202 offset:52224
	ds_read_b128 v[206:209], v202 offset:53248
	ds_read_b128 v[210:213], v202 offset:54272
	ds_read_b128 v[214:217], v202 offset:55296
	ds_read_b128 v[218:221], v202 offset:56320
	global_load_lds_dwordx4 v[222:223], off
	s_add_i32 m0, s63, 0x2000
	s_add_u32 s18, s18, 0x100080
	v_lshl_add_u64 v[222:223], v[224:225], 0, s[26:27]
	s_addc_u32 s19, s19, 0
	s_add_i32 s63, s82, s37
	global_load_lds_dwordx4 v[222:223], off
	v_lshl_add_u64 v[222:223], s[18:19], 0, v[148:149]
	s_mov_b32 m0, s63
	s_nop 0
	global_load_lds_dwordx4 v[222:223], off
	v_lshl_add_u64 v[222:223], s[18:19], 0, v[152:153]
	s_add_i32 m0, s63, 0x2000
	s_nop 0
	global_load_lds_dwordx4 v[222:223], off
	v_lshl_add_u64 v[222:223], v[226:227], 0, s[26:27]
	s_mov_b32 m0, s71
	s_nop 0
	global_load_lds_dwordx4 v[222:223], off
	v_lshl_add_u64 v[222:223], v[228:229], 0, s[26:27]
	s_mov_b32 m0, s72
	s_nop 0
	global_load_lds_dwordx4 v[222:223], off
	s_waitcnt vmcnt(8)
	s_waitcnt lgkmcnt(0)
	s_barrier
	s_waitcnt lgkmcnt(0)
	v_mfma_f32_16x16x32_bf16 v[74:77], v[46:49], v[180:183], v[74:77]
	v_mfma_f32_16x16x32_bf16 v[78:81], v[66:69], v[180:183], v[78:81]
	v_mfma_f32_16x16x32_bf16 v[58:61], v[46:49], v[188:191], v[58:61]
	v_mfma_f32_16x16x32_bf16 v[62:65], v[66:69], v[188:191], v[62:65]
	v_mfma_f32_16x16x32_bf16 v[26:29], v[46:49], v[206:209], v[26:29]
	v_mfma_f32_16x16x32_bf16 v[34:37], v[66:69], v[206:209], v[34:37]
	v_mfma_f32_16x16x32_bf16 v[10:13], v[46:49], v[214:217], v[10:13]
	v_mfma_f32_16x16x32_bf16 v[14:17], v[66:69], v[214:217], v[14:17]
	v_mfma_f32_16x16x32_bf16 v[74:77], v[54:57], v[184:187], v[74:77]
	v_mfma_f32_16x16x32_bf16 v[78:81], v[70:73], v[184:187], v[78:81]
	v_mfma_f32_16x16x32_bf16 v[58:61], v[54:57], v[192:195], v[58:61]
	v_mfma_f32_16x16x32_bf16 v[62:65], v[70:73], v[192:195], v[62:65]
	v_mfma_f32_16x16x32_bf16 v[26:29], v[54:57], v[210:213], v[26:29]
	v_mfma_f32_16x16x32_bf16 v[34:37], v[70:73], v[210:213], v[34:37]
	v_mfma_f32_16x16x32_bf16 v[10:13], v[54:57], v[218:221], v[10:13]
	v_mfma_f32_16x16x32_bf16 v[14:17], v[70:73], v[218:221], v[14:17]
	v_mfma_f32_16x16x32_bf16 v[30:33], v[164:167], v[180:183], v[30:33]
	v_mfma_f32_16x16x32_bf16 v[66:69], v[168:171], v[184:187], v[30:33]
	v_mfma_f32_16x16x32_bf16 v[30:33], v[172:175], v[180:183], v[38:41]
	v_mfma_f32_16x16x32_bf16 v[70:73], v[176:179], v[184:187], v[30:33]
	v_mfma_f32_16x16x32_bf16 v[30:33], v[164:167], v[188:191], v[42:45]
	v_mfma_f32_16x16x32_bf16 v[46:49], v[168:171], v[192:195], v[30:33]
	v_mfma_f32_16x16x32_bf16 v[30:33], v[172:175], v[188:191], v[50:53]
	v_mfma_f32_16x16x32_bf16 v[18:21], v[164:167], v[206:209], v[18:21]
	v_mfma_f32_16x16x32_bf16 v[22:25], v[172:175], v[206:209], v[22:25]
	v_mfma_f32_16x16x32_bf16 v[2:5], v[164:167], v[214:217], v[2:5]
	v_mfma_f32_16x16x32_bf16 v[6:9], v[172:175], v[214:217], v[6:9]
	v_mfma_f32_16x16x32_bf16 v[54:57], v[176:179], v[192:195], v[30:33]
	v_mfma_f32_16x16x32_bf16 v[18:21], v[168:171], v[210:213], v[18:21]
	v_mfma_f32_16x16x32_bf16 v[22:25], v[176:179], v[210:213], v[22:25]
	v_mfma_f32_16x16x32_bf16 v[2:5], v[168:171], v[218:221], v[2:5]
	v_mfma_f32_16x16x32_bf16 v[6:9], v[176:179], v[218:221], v[6:9]
	s_barrier
	s_add_i32 s61, s61, 2
	s_add_u32 s10, s10, 0x100
	s_addc_u32 s11, s11, 0
	s_add_u32 s16, s16, 0x100
	s_addc_u32 s17, s17, 0
	s_cmp_gt_u32 s61, 61
	s_cbranch_scc0 .LBB0_1647
	s_and_b64 vcc, exec, s[28:29]
	s_cbranch_vccz .LBB0_1650
	s_barrier

.LBB0_1921:
	ds_read_b128 v[130:133], v212
	ds_read_b128 v[134:137], v212 offset:1024
	ds_read_b128 v[138:141], v212 offset:2048
	ds_read_b128 v[142:145], v212 offset:3072
	ds_read_b128 v[146:149], v213
	ds_read_b128 v[150:153], v213 offset:1024
	ds_read_b128 v[154:157], v213 offset:2048
	ds_read_b128 v[158:161], v213 offset:3072
	s_add_u32 s40, s38, 0xfff00080
	s_addc_u32 s41, s39, -1
	s_cmp_eq_u32 s73, 60
	s_cselect_b32 s43, s31, s41
	s_cselect_b32 s42, s69, s40
	s_cselect_b32 s41, s29, s72
	s_cselect_b32 s40, s70, s71
	v_lshl_add_u64 v[216:217], s[38:39], 0, v[178:179]
	s_add_i32 m0, s19, 0xc000
	ds_read_b128 v[162:165], v214
	ds_read_b128 v[166:169], v214 offset:1024
	ds_read_b128 v[186:189], v214 offset:2048
	ds_read_b128 v[190:193], v214 offset:3072
	ds_read_b128 v[194:197], v214 offset:4096
	ds_read_b128 v[198:201], v214 offset:5120
	ds_read_b128 v[202:205], v214 offset:6144
	ds_read_b128 v[206:209], v214 offset:7168
	global_load_lds_dwordx4 v[216:217], off
	v_lshl_add_u64 v[216:217], s[38:39], 0, v[180:181]
	s_add_i32 m0, s19, 0xe000
	s_nop 0
	global_load_lds_dwordx4 v[216:217], off
	s_waitcnt vmcnt(8)
	s_waitcnt lgkmcnt(0)
	s_barrier
	s_waitcnt lgkmcnt(0)
	v_mfma_f32_16x16x32_bf16 v[126:129], v[130:133], v[162:165], v[126:129]
	v_mfma_f32_16x16x32_bf16 v[122:125], v[138:141], v[162:165], v[122:125]
	v_mfma_f32_16x16x32_bf16 v[110:113], v[130:133], v[186:189], v[110:113]
	v_mfma_f32_16x16x32_bf16 v[106:109], v[138:141], v[186:189], v[106:109]
	v_mfma_f32_16x16x32_bf16 v[94:97], v[130:133], v[194:197], v[94:97]
	v_mfma_f32_16x16x32_bf16 v[90:93], v[138:141], v[194:197], v[90:93]
	v_mfma_f32_16x16x32_bf16 v[78:81], v[130:133], v[202:205], v[78:81]
	v_mfma_f32_16x16x32_bf16 v[74:77], v[138:141], v[202:205], v[74:77]
	v_mfma_f32_16x16x32_bf16 v[126:129], v[134:137], v[166:169], v[126:129]
	v_mfma_f32_16x16x32_bf16 v[122:125], v[142:145], v[166:169], v[122:125]
	v_mfma_f32_16x16x32_bf16 v[110:113], v[134:137], v[190:193], v[110:113]
	v_mfma_f32_16x16x32_bf16 v[106:109], v[142:145], v[190:193], v[106:109]
	v_mfma_f32_16x16x32_bf16 v[94:97], v[134:137], v[198:201], v[94:97]
	v_mfma_f32_16x16x32_bf16 v[90:93], v[142:145], v[198:201], v[90:93]
	v_mfma_f32_16x16x32_bf16 v[78:81], v[134:137], v[206:209], v[78:81]
	v_mfma_f32_16x16x32_bf16 v[74:77], v[142:145], v[206:209], v[74:77]
	v_mfma_f32_16x16x32_bf16 v[118:121], v[146:149], v[162:165], v[118:121]
	v_mfma_f32_16x16x32_bf16 v[114:117], v[154:157], v[162:165], v[114:117]
	v_mfma_f32_16x16x32_bf16 v[102:105], v[146:149], v[186:189], v[102:105]
	v_mfma_f32_16x16x32_bf16 v[98:101], v[154:157], v[186:189], v[98:101]
	v_mfma_f32_16x16x32_bf16 v[86:89], v[146:149], v[194:197], v[86:89]
	v_mfma_f32_16x16x32_bf16 v[82:85], v[154:157], v[194:197], v[82:85]
	v_mfma_f32_16x16x32_bf16 v[70:73], v[146:149], v[202:205], v[70:73]
	v_mfma_f32_16x16x32_bf16 v[66:69], v[154:157], v[202:205], v[66:69]
	v_mfma_f32_16x16x32_bf16 v[118:121], v[150:153], v[166:169], v[118:121]
	v_mfma_f32_16x16x32_bf16 v[114:117], v[158:161], v[166:169], v[114:117]
	v_mfma_f32_16x16x32_bf16 v[102:105], v[150:153], v[190:193], v[102:105]
	v_mfma_f32_16x16x32_bf16 v[98:101], v[158:161], v[190:193], v[98:101]
	v_mfma_f32_16x16x32_bf16 v[86:89], v[150:153], v[198:201], v[86:89]
	v_mfma_f32_16x16x32_bf16 v[82:85], v[158:161], v[198:201], v[82:85]
	v_mfma_f32_16x16x32_bf16 v[70:73], v[150:153], v[206:209], v[70:73]
	v_mfma_f32_16x16x32_bf16 v[66:69], v[158:161], v[206:209], v[66:69]
	s_barrier
	s_add_i32 s76, s57, s17
	v_lshl_add_u64 v[216:217], s[40:41], 0, v[172:173]
	s_mov_b32 m0, s76
	ds_read_b128 v[162:165], v214 offset:16384
	ds_read_b128 v[166:169], v214 offset:17408
	ds_read_b128 v[186:189], v214 offset:18432
	ds_read_b128 v[190:193], v214 offset:19456
	ds_read_b128 v[194:197], v214 offset:20480
	ds_read_b128 v[198:201], v214 offset:21504
	ds_read_b128 v[202:205], v214 offset:22528
	ds_read_b128 v[206:209], v214 offset:23552
	global_load_lds_dwordx4 v[216:217], off
	s_add_i32 m0, s76, 0x2000
	s_add_u32 s76, s40, 0x100000
	v_lshl_add_u64 v[218:219], s[40:41], 0, v[176:177]
	s_addc_u32 s77, s41, 0
	s_add_i32 s78, s60, s17
	global_load_lds_dwordx4 v[218:219], off
	v_lshl_add_u64 v[220:221], s[76:77], 0, v[172:173]
	s_mov_b32 m0, s78
	v_lshl_add_u64 v[222:223], s[42:43], 0, v[174:175]
	global_load_lds_dwordx4 v[220:221], off
	v_lshl_add_u64 v[220:221], s[76:77], 0, v[176:177]
	s_add_i32 m0, s78, 0x2000
	s_nop 0
	global_load_lds_dwordx4 v[220:221], off
	v_lshl_add_u64 v[220:221], s[42:43], 0, v[170:171]
	s_mov_b32 m0, s19
	s_nop 0
	global_load_lds_dwordx4 v[220:221], off
	s_mov_b32 m0, s44
	s_nop 0
	global_load_lds_dwordx4 v[222:223], off
	s_waitcnt vmcnt(8)
	s_waitcnt lgkmcnt(0)
	s_barrier
	s_waitcnt lgkmcnt(0)
	v_mfma_f32_16x16x32_bf16 v[62:65], v[130:133], v[162:165], v[62:65]
	v_mfma_f32_16x16x32_bf16 v[58:61], v[138:141], v[162:165], v[58:61]
	v_mfma_f32_16x16x32_bf16 v[46:49], v[130:133], v[186:189], v[46:49]
	v_mfma_f32_16x16x32_bf16 v[42:45], v[138:141], v[186:189], v[42:45]
	v_mfma_f32_16x16x32_bf16 v[30:33], v[130:133], v[194:197], v[30:33]
	v_mfma_f32_16x16x32_bf16 v[26:29], v[138:141], v[194:197], v[26:29]
	v_mfma_f32_16x16x32_bf16 v[14:17], v[130:133], v[202:205], v[14:17]
	v_mfma_f32_16x16x32_bf16 v[10:13], v[138:141], v[202:205], v[10:13]
	v_mfma_f32_16x16x32_bf16 v[62:65], v[134:137], v[166:169], v[62:65]
	v_mfma_f32_16x16x32_bf16 v[58:61], v[142:145], v[166:169], v[58:61]
	v_mfma_f32_16x16x32_bf16 v[46:49], v[134:137], v[190:193], v[46:49]
	v_mfma_f32_16x16x32_bf16 v[42:45], v[142:145], v[190:193], v[42:45]
	v_mfma_f32_16x16x32_bf16 v[30:33], v[134:137], v[198:201], v[30:33]
	v_mfma_f32_16x16x32_bf16 v[26:29], v[142:145], v[198:201], v[26:29]
	v_mfma_f32_16x16x32_bf16 v[14:17], v[134:137], v[206:209], v[14:17]
	v_mfma_f32_16x16x32_bf16 v[10:13], v[142:145], v[206:209], v[10:13]
	v_mfma_f32_16x16x32_bf16 v[54:57], v[146:149], v[162:165], v[54:57]
	v_mfma_f32_16x16x32_bf16 v[50:53], v[154:157], v[162:165], v[50:53]
	v_mfma_f32_16x16x32_bf16 v[38:41], v[146:149], v[186:189], v[38:41]
	v_mfma_f32_16x16x32_bf16 v[34:37], v[154:157], v[186:189], v[34:37]
	v_mfma_f32_16x16x32_bf16 v[22:25], v[146:149], v[194:197], v[22:25]
	v_mfma_f32_16x16x32_bf16 v[18:21], v[154:157], v[194:197], v[18:21]
	v_mfma_f32_16x16x32_bf16 v[6:9], v[146:149], v[202:205], v[6:9]
	v_mfma_f32_16x16x32_bf16 v[2:5], v[154:157], v[202:205], v[2:5]
	v_mfma_f32_16x16x32_bf16 v[54:57], v[150:153], v[166:169], v[54:57]
	v_mfma_f32_16x16x32_bf16 v[50:53], v[158:161], v[166:169], v[50:53]
	v_mfma_f32_16x16x32_bf16 v[38:41], v[150:153], v[190:193], v[38:41]
	v_mfma_f32_16x16x32_bf16 v[34:37], v[158:161], v[190:193], v[34:37]
	v_mfma_f32_16x16x32_bf16 v[22:25], v[150:153], v[198:201], v[22:25]
	v_mfma_f32_16x16x32_bf16 v[18:21], v[158:161], v[198:201], v[18:21]
	v_mfma_f32_16x16x32_bf16 v[6:9], v[150:153], v[206:209], v[6:9]
	v_mfma_f32_16x16x32_bf16 v[2:5], v[158:161], v[206:209], v[2:5]
	s_barrier
	s_add_i32 s76, 0, 0x18000
	s_add_i32 s77, 0, 0x1c000
	v_add_u32_e32 v142, s76, v211
	v_add_u32_e32 v158, s77, v211
	ds_read_b128 v[130:133], v142
	ds_read_b128 v[134:137], v142 offset:1024
	ds_read_b128 v[138:141], v142 offset:2048
	ds_read_b128 v[142:145], v142 offset:3072
	ds_read_b128 v[146:149], v158
	ds_read_b128 v[150:153], v158 offset:1024
	ds_read_b128 v[154:157], v158 offset:2048
	ds_read_b128 v[158:161], v158 offset:3072
	s_add_u32 s42, s42, 0x100000
	s_addc_u32 s43, s43, 0
	s_mov_b32 m0, s45
	v_lshl_add_u64 v[224:225], s[42:43], 0, v[170:171]
	ds_read_b128 v[162:165], v214 offset:32768
	ds_read_b128 v[166:169], v214 offset:33792
	ds_read_b128 v[186:189], v214 offset:34816
	ds_read_b128 v[190:193], v214 offset:35840
	ds_read_b128 v[194:197], v214 offset:36864
	ds_read_b128 v[198:201], v214 offset:37888
	ds_read_b128 v[202:205], v214 offset:38912
	ds_read_b128 v[206:209], v214 offset:39936
	global_load_lds_dwordx4 v[224:225], off
	v_lshl_add_u64 v[224:225], s[42:43], 0, v[174:175]
	s_mov_b32 m0, s46
	s_nop 0
	global_load_lds_dwordx4 v[224:225], off
	s_waitcnt vmcnt(8)
	s_waitcnt lgkmcnt(0)
	s_barrier
	s_waitcnt lgkmcnt(0)
	v_mfma_f32_16x16x32_bf16 v[126:129], v[130:133], v[162:165], v[126:129]
	v_mfma_f32_16x16x32_bf16 v[122:125], v[138:141], v[162:165], v[122:125]
	v_mfma_f32_16x16x32_bf16 v[110:113], v[130:133], v[186:189], v[110:113]
	v_mfma_f32_16x16x32_bf16 v[106:109], v[138:141], v[186:189], v[106:109]
	v_mfma_f32_16x16x32_bf16 v[94:97], v[130:133], v[194:197], v[94:97]
	v_mfma_f32_16x16x32_bf16 v[90:93], v[138:141], v[194:197], v[90:93]
	v_mfma_f32_16x16x32_bf16 v[78:81], v[130:133], v[202:205], v[78:81]
	v_mfma_f32_16x16x32_bf16 v[74:77], v[138:141], v[202:205], v[74:77]
	v_mfma_f32_16x16x32_bf16 v[126:129], v[134:137], v[166:169], v[126:129]
	v_mfma_f32_16x16x32_bf16 v[122:125], v[142:145], v[166:169], v[122:125]
	v_mfma_f32_16x16x32_bf16 v[110:113], v[134:137], v[190:193], v[110:113]
	v_mfma_f32_16x16x32_bf16 v[106:109], v[142:145], v[190:193], v[106:109]
	v_mfma_f32_16x16x32_bf16 v[94:97], v[134:137], v[198:201], v[94:97]
	v_mfma_f32_16x16x32_bf16 v[90:93], v[142:145], v[198:201], v[90:93]
	v_mfma_f32_16x16x32_bf16 v[78:81], v[134:137], v[206:209], v[78:81]
	v_mfma_f32_16x16x32_bf16 v[74:77], v[142:145], v[206:209], v[74:77]
	v_mfma_f32_16x16x32_bf16 v[118:121], v[146:149], v[162:165], v[118:121]
	v_mfma_f32_16x16x32_bf16 v[114:117], v[154:157], v[162:165], v[114:117]
	v_mfma_f32_16x16x32_bf16 v[102:105], v[146:149], v[186:189], v[102:105]
	v_mfma_f32_16x16x32_bf16 v[98:101], v[154:157], v[186:189], v[98:101]
	v_mfma_f32_16x16x32_bf16 v[86:89], v[146:149], v[194:197], v[86:89]
	v_mfma_f32_16x16x32_bf16 v[82:85], v[154:157], v[194:197], v[82:85]
	v_mfma_f32_16x16x32_bf16 v[70:73], v[146:149], v[202:205], v[70:73]
	v_mfma_f32_16x16x32_bf16 v[66:69], v[154:157], v[202:205], v[66:69]
	v_mfma_f32_16x16x32_bf16 v[118:121], v[150:153], v[166:169], v[118:121]
	v_mfma_f32_16x16x32_bf16 v[114:117], v[158:161], v[166:169], v[114:117]
	v_mfma_f32_16x16x32_bf16 v[102:105], v[150:153], v[190:193], v[102:105]
	v_mfma_f32_16x16x32_bf16 v[98:101], v[158:161], v[190:193], v[98:101]
	v_mfma_f32_16x16x32_bf16 v[86:89], v[150:153], v[198:201], v[86:89]
	v_mfma_f32_16x16x32_bf16 v[82:85], v[158:161], v[198:201], v[82:85]
	v_mfma_f32_16x16x32_bf16 v[70:73], v[150:153], v[206:209], v[70:73]
	v_mfma_f32_16x16x32_bf16 v[66:69], v[158:161], v[206:209], v[66:69]
	s_barrier
	s_add_i32 s42, s76, s17
	v_lshl_add_u64 v[216:217], v[216:217], 0, s[8:9]
	s_mov_b32 m0, s42
	ds_read_b128 v[162:165], v214 offset:49152
	ds_read_b128 v[166:169], v214 offset:50176
	ds_read_b128 v[186:189], v214 offset:51200
	ds_read_b128 v[190:193], v214 offset:52224
	ds_read_b128 v[194:197], v214 offset:53248
	ds_read_b128 v[198:201], v214 offset:54272
	ds_read_b128 v[202:205], v214 offset:55296
	ds_read_b128 v[206:209], v214 offset:56320
	global_load_lds_dwordx4 v[216:217], off
	s_add_i32 m0, s42, 0x2000
	s_add_u32 s40, s40, 0x100080
	v_lshl_add_u64 v[216:217], v[218:219], 0, s[8:9]
	s_addc_u32 s41, s41, 0
	s_add_i32 s42, s77, s17
	global_load_lds_dwordx4 v[216:217], off
	v_lshl_add_u64 v[216:217], s[40:41], 0, v[172:173]
	s_mov_b32 m0, s42
	s_nop 0
	global_load_lds_dwordx4 v[216:217], off
	v_lshl_add_u64 v[216:217], s[40:41], 0, v[176:177]
	s_add_i32 m0, s42, 0x2000
	s_nop 0
	global_load_lds_dwordx4 v[216:217], off
	v_lshl_add_u64 v[216:217], v[220:221], 0, s[8:9]
	s_mov_b32 m0, s50
	s_nop 0
	global_load_lds_dwordx4 v[216:217], off
	v_lshl_add_u64 v[216:217], v[222:223], 0, s[8:9]
	s_mov_b32 m0, s51
	s_nop 0
	global_load_lds_dwordx4 v[216:217], off
	s_waitcnt vmcnt(8)
	s_waitcnt lgkmcnt(0)
	s_barrier
	s_waitcnt lgkmcnt(0)
	v_mfma_f32_16x16x32_bf16 v[62:65], v[130:133], v[162:165], v[62:65]
	v_mfma_f32_16x16x32_bf16 v[58:61], v[138:141], v[162:165], v[58:61]
	v_mfma_f32_16x16x32_bf16 v[46:49], v[130:133], v[186:189], v[46:49]
	v_mfma_f32_16x16x32_bf16 v[42:45], v[138:141], v[186:189], v[42:45]
	v_mfma_f32_16x16x32_bf16 v[30:33], v[130:133], v[194:197], v[30:33]
	v_mfma_f32_16x16x32_bf16 v[26:29], v[138:141], v[194:197], v[26:29]
	v_mfma_f32_16x16x32_bf16 v[14:17], v[130:133], v[202:205], v[14:17]
	v_mfma_f32_16x16x32_bf16 v[10:13], v[138:141], v[202:205], v[10:13]
	v_mfma_f32_16x16x32_bf16 v[62:65], v[134:137], v[166:169], v[62:65]
	v_mfma_f32_16x16x32_bf16 v[58:61], v[142:145], v[166:169], v[58:61]
	v_mfma_f32_16x16x32_bf16 v[46:49], v[134:137], v[190:193], v[46:49]
	v_mfma_f32_16x16x32_bf16 v[42:45], v[142:145], v[190:193], v[42:45]
	v_mfma_f32_16x16x32_bf16 v[30:33], v[134:137], v[198:201], v[30:33]
	v_mfma_f32_16x16x32_bf16 v[26:29], v[142:145], v[198:201], v[26:29]
	v_mfma_f32_16x16x32_bf16 v[14:17], v[134:137], v[206:209], v[14:17]
	v_mfma_f32_16x16x32_bf16 v[10:13], v[142:145], v[206:209], v[10:13]
	v_mfma_f32_16x16x32_bf16 v[54:57], v[146:149], v[162:165], v[54:57]
	v_mfma_f32_16x16x32_bf16 v[50:53], v[154:157], v[162:165], v[50:53]
	v_mfma_f32_16x16x32_bf16 v[38:41], v[146:149], v[186:189], v[38:41]
	v_mfma_f32_16x16x32_bf16 v[34:37], v[154:157], v[186:189], v[34:37]
	v_mfma_f32_16x16x32_bf16 v[22:25], v[146:149], v[194:197], v[22:25]
	v_mfma_f32_16x16x32_bf16 v[18:21], v[154:157], v[194:197], v[18:21]
	v_mfma_f32_16x16x32_bf16 v[6:9], v[146:149], v[202:205], v[6:9]
	v_mfma_f32_16x16x32_bf16 v[2:5], v[154:157], v[202:205], v[2:5]
	v_mfma_f32_16x16x32_bf16 v[54:57], v[150:153], v[166:169], v[54:57]
	v_mfma_f32_16x16x32_bf16 v[50:53], v[158:161], v[166:169], v[50:53]
	v_mfma_f32_16x16x32_bf16 v[38:41], v[150:153], v[190:193], v[38:41]
	v_mfma_f32_16x16x32_bf16 v[34:37], v[158:161], v[190:193], v[34:37]
	v_mfma_f32_16x16x32_bf16 v[22:25], v[150:153], v[198:201], v[22:25]
	v_mfma_f32_16x16x32_bf16 v[18:21], v[158:161], v[198:201], v[18:21]
	v_mfma_f32_16x16x32_bf16 v[6:9], v[150:153], v[206:209], v[6:9]
	v_mfma_f32_16x16x32_bf16 v[2:5], v[158:161], v[206:209], v[2:5]
	s_barrier
	s_add_i32 s73, s73, 2
	s_add_u32 s38, s38, 0x100
	s_addc_u32 s39, s39, 0
	s_add_u32 s71, s71, 0x100
	s_addc_u32 s72, s72, 0
	s_cmp_gt_u32 s73, 61
	s_cbranch_scc0 .LBB0_1921
	s_and_b64 vcc, exec, s[10:11]
	s_cbranch_vccz .LBB0_1924
	s_barrier

.LBB0_2056:
	ds_read_b128 v[130:133], v234
	ds_read_b128 v[134:137], v234 offset:1024
	ds_read_b128 v[162:165], v234 offset:2048
	ds_read_b128 v[166:169], v234 offset:3072
	ds_read_b128 v[170:173], v235
	ds_read_b128 v[174:177], v235 offset:1024
	ds_read_b128 v[178:181], v235 offset:2048
	ds_read_b128 v[182:185], v235 offset:3072
	s_add_u32 s4, s2, 0x100
	s_addc_u32 s5, s3, 0
	s_cmp_eq_u32 s93, 28
	s_cselect_b32 s43, s31, s5
	s_cselect_b32 s42, s87, s4
	s_cselect_b32 s19, s29, s92
	s_cselect_b32 s18, s90, s91
	v_lshl_add_u64 v[218:219], s[2:3], 0, v[154:155]
	s_add_i32 m0, s49, 0xc000
	ds_read_b128 v[186:189], v236
	ds_read_b128 v[190:193], v236 offset:1024
	ds_read_b128 v[194:197], v236 offset:2048
	ds_read_b128 v[198:201], v236 offset:3072
	ds_read_b128 v[202:205], v236 offset:4096
	ds_read_b128 v[206:209], v236 offset:5120
	ds_read_b128 v[210:213], v236 offset:6144
	ds_read_b128 v[214:217], v236 offset:7168
	global_load_lds_dwordx4 v[218:219], off
	v_lshl_add_u64 v[218:219], s[2:3], 0, v[156:157]
	s_add_i32 m0, s49, 0xe000
	s_nop 0
	global_load_lds_dwordx4 v[218:219], off
	s_waitcnt vmcnt(8)
	s_waitcnt lgkmcnt(0)
	s_barrier
	s_waitcnt lgkmcnt(0)
	v_mfma_i32_16x16x64_i8 v[118:121], v[130:133], v[186:189], v[118:121]
	v_mfma_i32_16x16x64_i8 v[102:105], v[162:165], v[186:189], v[102:105]
	v_mfma_i32_16x16x64_i8 v[114:117], v[130:133], v[194:197], v[114:117]
	v_mfma_i32_16x16x64_i8 v[98:101], v[162:165], v[194:197], v[98:101]
	v_mfma_i32_16x16x64_i8 v[126:129], v[130:133], v[202:205], v[126:129]
	v_mfma_i32_16x16x64_i8 v[110:113], v[162:165], v[202:205], v[110:113]
	v_mfma_i32_16x16x64_i8 v[122:125], v[130:133], v[210:213], v[122:125]
	v_mfma_i32_16x16x64_i8 v[106:109], v[162:165], v[210:213], v[106:109]
	v_mfma_i32_16x16x64_i8 v[118:121], v[134:137], v[190:193], v[118:121]
	v_mfma_i32_16x16x64_i8 v[102:105], v[166:169], v[190:193], v[102:105]
	v_mfma_i32_16x16x64_i8 v[114:117], v[134:137], v[198:201], v[114:117]
	v_mfma_i32_16x16x64_i8 v[98:101], v[166:169], v[198:201], v[98:101]
	v_mfma_i32_16x16x64_i8 v[126:129], v[134:137], v[206:209], v[126:129]
	v_mfma_i32_16x16x64_i8 v[110:113], v[166:169], v[206:209], v[110:113]
	v_mfma_i32_16x16x64_i8 v[122:125], v[134:137], v[214:217], v[122:125]
	v_mfma_i32_16x16x64_i8 v[106:109], v[166:169], v[214:217], v[106:109]
	v_mfma_i32_16x16x64_i8 v[86:89], v[170:173], v[186:189], v[86:89]
	v_mfma_i32_16x16x64_i8 v[70:73], v[178:181], v[186:189], v[70:73]
	v_mfma_i32_16x16x64_i8 v[82:85], v[170:173], v[194:197], v[82:85]
	v_mfma_i32_16x16x64_i8 v[66:69], v[178:181], v[194:197], v[66:69]
	v_mfma_i32_16x16x64_i8 v[94:97], v[170:173], v[202:205], v[94:97]
	v_mfma_i32_16x16x64_i8 v[78:81], v[178:181], v[202:205], v[78:81]
	v_mfma_i32_16x16x64_i8 v[90:93], v[170:173], v[210:213], v[90:93]
	v_mfma_i32_16x16x64_i8 v[74:77], v[178:181], v[210:213], v[74:77]
	v_mfma_i32_16x16x64_i8 v[86:89], v[174:177], v[190:193], v[86:89]
	v_mfma_i32_16x16x64_i8 v[70:73], v[182:185], v[190:193], v[70:73]
	v_mfma_i32_16x16x64_i8 v[82:85], v[174:177], v[198:201], v[82:85]
	v_mfma_i32_16x16x64_i8 v[66:69], v[182:185], v[198:201], v[66:69]
	v_mfma_i32_16x16x64_i8 v[94:97], v[174:177], v[206:209], v[94:97]
	v_mfma_i32_16x16x64_i8 v[78:81], v[182:185], v[206:209], v[78:81]
	v_mfma_i32_16x16x64_i8 v[90:93], v[174:177], v[214:217], v[90:93]
	v_mfma_i32_16x16x64_i8 v[74:77], v[182:185], v[214:217], v[74:77]
	s_barrier
	s_add_i32 s2, s82, s47
	v_lshl_add_u64 v[218:219], s[18:19], 0, v[144:145]
	s_mov_b32 m0, s2
	ds_read_b128 v[186:189], v236 offset:16384
	ds_read_b128 v[190:193], v236 offset:17408
	ds_read_b128 v[194:197], v236 offset:18432
	ds_read_b128 v[198:201], v236 offset:19456
	ds_read_b128 v[202:205], v236 offset:20480
	ds_read_b128 v[206:209], v236 offset:21504
	ds_read_b128 v[210:213], v236 offset:22528
	ds_read_b128 v[214:217], v236 offset:23552
	global_load_lds_dwordx4 v[218:219], off
	s_add_i32 m0, s2, 0x2000
	s_add_u32 s2, s18, 0x80000
	v_lshl_add_u64 v[220:221], s[18:19], 0, v[148:149]
	s_addc_u32 s3, s19, 0
	s_add_i32 s94, s16, s47
	global_load_lds_dwordx4 v[220:221], off
	v_lshl_add_u64 v[222:223], s[2:3], 0, v[144:145]
	s_mov_b32 m0, s94
	v_lshl_add_u64 v[224:225], s[42:43], 0, v[146:147]
	global_load_lds_dwordx4 v[222:223], off
	v_lshl_add_u64 v[222:223], s[2:3], 0, v[148:149]
	s_add_i32 m0, s94, 0x2000
	s_nop 0
	global_load_lds_dwordx4 v[222:223], off
	v_lshl_add_u64 v[222:223], s[42:43], 0, v[142:143]
	s_mov_b32 m0, s49
	s_nop 0
	global_load_lds_dwordx4 v[222:223], off
	s_mov_b32 m0, s50
	s_nop 0
	global_load_lds_dwordx4 v[224:225], off
	s_waitcnt vmcnt(8)
	s_waitcnt lgkmcnt(0)
	s_barrier
	s_waitcnt lgkmcnt(0)
	v_mfma_i32_16x16x64_i8 v[54:57], v[130:133], v[186:189], v[54:57]
	v_mfma_i32_16x16x64_i8 v[18:21], v[162:165], v[186:189], v[18:21]
	v_mfma_i32_16x16x64_i8 v[50:53], v[130:133], v[194:197], v[50:53]
	v_mfma_i32_16x16x64_i8 v[22:25], v[162:165], v[194:197], v[22:25]
	v_mfma_i32_16x16x64_i8 v[62:65], v[130:133], v[202:205], v[62:65]
	v_mfma_i32_16x16x64_i8 v[30:33], v[162:165], v[202:205], v[30:33]
	v_mfma_i32_16x16x64_i8 v[58:61], v[130:133], v[210:213], v[58:61]
	v_mfma_i32_16x16x64_i8 v[26:29], v[162:165], v[210:213], v[26:29]
	v_mfma_i32_16x16x64_i8 v[54:57], v[134:137], v[190:193], v[54:57]
	v_mfma_i32_16x16x64_i8 v[18:21], v[166:169], v[190:193], v[18:21]
	v_mfma_i32_16x16x64_i8 v[50:53], v[134:137], v[198:201], v[50:53]
	v_mfma_i32_16x16x64_i8 v[22:25], v[166:169], v[198:201], v[22:25]
	v_mfma_i32_16x16x64_i8 v[62:65], v[134:137], v[206:209], v[62:65]
	v_mfma_i32_16x16x64_i8 v[30:33], v[166:169], v[206:209], v[30:33]
	v_mfma_i32_16x16x64_i8 v[58:61], v[134:137], v[214:217], v[58:61]
	v_mfma_i32_16x16x64_i8 v[26:29], v[166:169], v[214:217], v[26:29]
	v_mfma_i32_16x16x64_i8 v[46:49], v[170:173], v[186:189], v[46:49]
	v_mfma_i32_16x16x64_i8 v[14:17], v[178:181], v[186:189], v[14:17]
	v_mfma_i32_16x16x64_i8 v[42:45], v[170:173], v[194:197], v[42:45]
	v_mfma_i32_16x16x64_i8 v[10:13], v[178:181], v[194:197], v[10:13]
	v_mfma_i32_16x16x64_i8 v[38:41], v[170:173], v[202:205], v[38:41]
	v_mfma_i32_16x16x64_i8 v[6:9], v[178:181], v[202:205], v[6:9]
	v_mfma_i32_16x16x64_i8 v[34:37], v[170:173], v[210:213], v[34:37]
	v_mfma_i32_16x16x64_i8 v[2:5], v[178:181], v[210:213], v[2:5]
	v_mfma_i32_16x16x64_i8 v[46:49], v[174:177], v[190:193], v[46:49]
	v_mfma_i32_16x16x64_i8 v[14:17], v[182:185], v[190:193], v[14:17]
	v_mfma_i32_16x16x64_i8 v[42:45], v[174:177], v[198:201], v[42:45]
	v_mfma_i32_16x16x64_i8 v[10:13], v[182:185], v[198:201], v[10:13]
	v_mfma_i32_16x16x64_i8 v[38:41], v[174:177], v[206:209], v[38:41]
	v_mfma_i32_16x16x64_i8 v[6:9], v[182:185], v[206:209], v[6:9]
	v_mfma_i32_16x16x64_i8 v[34:37], v[174:177], v[214:217], v[34:37]
	v_mfma_i32_16x16x64_i8 v[2:5], v[182:185], v[214:217], v[2:5]
	s_barrier
	s_add_i32 s94, 0, 0x18000
	s_add_i32 s95, 0, 0x1c000
	v_add_u32_e32 v166, s94, v232
	v_add_u32_e32 v182, s95, v232
	ds_read_b128 v[130:133], v166
	ds_read_b128 v[134:137], v166 offset:1024
	ds_read_b128 v[162:165], v166 offset:2048
	ds_read_b128 v[166:169], v166 offset:3072
	ds_read_b128 v[170:173], v182
	ds_read_b128 v[174:177], v182 offset:1024
	ds_read_b128 v[178:181], v182 offset:2048
	ds_read_b128 v[182:185], v182 offset:3072
	s_add_u32 s2, s42, 0x80000
	s_addc_u32 s3, s43, 0
	s_mov_b32 m0, s51
	v_lshl_add_u64 v[226:227], s[2:3], 0, v[142:143]
	ds_read_b128 v[186:189], v236 offset:32768
	ds_read_b128 v[190:193], v236 offset:33792
	ds_read_b128 v[194:197], v236 offset:34816
	ds_read_b128 v[198:201], v236 offset:35840
	ds_read_b128 v[202:205], v236 offset:36864
	ds_read_b128 v[206:209], v236 offset:37888
	ds_read_b128 v[210:213], v236 offset:38912
	ds_read_b128 v[214:217], v236 offset:39936
	global_load_lds_dwordx4 v[226:227], off
	v_lshl_add_u64 v[226:227], s[2:3], 0, v[146:147]
	s_mov_b32 m0, s54
	s_nop 0
	global_load_lds_dwordx4 v[226:227], off
	s_waitcnt vmcnt(8)
	s_waitcnt lgkmcnt(0)
	s_barrier
	s_waitcnt lgkmcnt(0)
	v_mfma_i32_16x16x64_i8 v[118:121], v[130:133], v[186:189], v[118:121]
	v_mfma_i32_16x16x64_i8 v[102:105], v[162:165], v[186:189], v[102:105]
	v_mfma_i32_16x16x64_i8 v[114:117], v[130:133], v[194:197], v[114:117]
	v_mfma_i32_16x16x64_i8 v[98:101], v[162:165], v[194:197], v[98:101]
	v_mfma_i32_16x16x64_i8 v[126:129], v[130:133], v[202:205], v[126:129]
	v_mfma_i32_16x16x64_i8 v[110:113], v[162:165], v[202:205], v[110:113]
	v_mfma_i32_16x16x64_i8 v[122:125], v[130:133], v[210:213], v[122:125]
	v_mfma_i32_16x16x64_i8 v[106:109], v[162:165], v[210:213], v[106:109]
	v_mfma_i32_16x16x64_i8 v[118:121], v[134:137], v[190:193], v[118:121]
	v_mfma_i32_16x16x64_i8 v[102:105], v[166:169], v[190:193], v[102:105]
	v_mfma_i32_16x16x64_i8 v[114:117], v[134:137], v[198:201], v[114:117]
	v_mfma_i32_16x16x64_i8 v[98:101], v[166:169], v[198:201], v[98:101]
	v_mfma_i32_16x16x64_i8 v[126:129], v[134:137], v[206:209], v[126:129]
	v_mfma_i32_16x16x64_i8 v[110:113], v[166:169], v[206:209], v[110:113]
	v_mfma_i32_16x16x64_i8 v[122:125], v[134:137], v[214:217], v[122:125]
	v_mfma_i32_16x16x64_i8 v[106:109], v[166:169], v[214:217], v[106:109]
	v_mfma_i32_16x16x64_i8 v[86:89], v[170:173], v[186:189], v[86:89]
	v_mfma_i32_16x16x64_i8 v[70:73], v[178:181], v[186:189], v[70:73]
	v_mfma_i32_16x16x64_i8 v[82:85], v[170:173], v[194:197], v[82:85]
	v_mfma_i32_16x16x64_i8 v[66:69], v[178:181], v[194:197], v[66:69]
	v_mfma_i32_16x16x64_i8 v[94:97], v[170:173], v[202:205], v[94:97]
	v_mfma_i32_16x16x64_i8 v[78:81], v[178:181], v[202:205], v[78:81]
	v_mfma_i32_16x16x64_i8 v[90:93], v[170:173], v[210:213], v[90:93]
	v_mfma_i32_16x16x64_i8 v[74:77], v[178:181], v[210:213], v[74:77]
	v_mfma_i32_16x16x64_i8 v[86:89], v[174:177], v[190:193], v[86:89]
	v_mfma_i32_16x16x64_i8 v[70:73], v[182:185], v[190:193], v[70:73]
	v_mfma_i32_16x16x64_i8 v[82:85], v[174:177], v[198:201], v[82:85]
	v_mfma_i32_16x16x64_i8 v[66:69], v[182:185], v[198:201], v[66:69]
	v_mfma_i32_16x16x64_i8 v[94:97], v[174:177], v[206:209], v[94:97]
	v_mfma_i32_16x16x64_i8 v[78:81], v[182:185], v[206:209], v[78:81]
	v_mfma_i32_16x16x64_i8 v[90:93], v[174:177], v[214:217], v[90:93]
	v_mfma_i32_16x16x64_i8 v[74:77], v[182:185], v[214:217], v[74:77]
	s_barrier
	s_add_i32 s2, s94, s47
	v_lshl_add_u64 v[218:219], v[218:219], 0, s[14:15]
	s_mov_b32 m0, s2
	ds_read_b128 v[186:189], v236 offset:49152
	ds_read_b128 v[190:193], v236 offset:50176
	ds_read_b128 v[194:197], v236 offset:51200
	ds_read_b128 v[198:201], v236 offset:52224
	ds_read_b128 v[202:205], v236 offset:53248
	ds_read_b128 v[206:209], v236 offset:54272
	ds_read_b128 v[210:213], v236 offset:55296
	ds_read_b128 v[214:217], v236 offset:56320
	global_load_lds_dwordx4 v[218:219], off
	s_add_i32 m0, s2, 0x2000
	s_add_u32 s2, s18, 0x80080
	v_lshl_add_u64 v[218:219], v[220:221], 0, s[14:15]
	s_addc_u32 s3, s19, 0
	s_add_i32 s18, s95, s47
	global_load_lds_dwordx4 v[218:219], off
	v_lshl_add_u64 v[218:219], s[2:3], 0, v[144:145]
	s_mov_b32 m0, s18
	s_nop 0
	global_load_lds_dwordx4 v[218:219], off
	v_lshl_add_u64 v[218:219], s[2:3], 0, v[148:149]
	s_add_i32 m0, s18, 0x2000
	s_nop 0
	global_load_lds_dwordx4 v[218:219], off
	v_lshl_add_u64 v[218:219], v[222:223], 0, s[14:15]
	s_mov_b32 m0, s63
	s_nop 0
	global_load_lds_dwordx4 v[218:219], off
	v_lshl_add_u64 v[218:219], v[224:225], 0, s[14:15]
	s_mov_b32 m0, s64
	s_nop 0
	global_load_lds_dwordx4 v[218:219], off
	s_waitcnt vmcnt(8)
	s_waitcnt lgkmcnt(0)
	s_barrier
	s_waitcnt lgkmcnt(0)
	v_mfma_i32_16x16x64_i8 v[54:57], v[130:133], v[186:189], v[54:57]
	v_mfma_i32_16x16x64_i8 v[18:21], v[162:165], v[186:189], v[18:21]
	v_mfma_i32_16x16x64_i8 v[50:53], v[130:133], v[194:197], v[50:53]
	v_mfma_i32_16x16x64_i8 v[22:25], v[162:165], v[194:197], v[22:25]
	v_mfma_i32_16x16x64_i8 v[62:65], v[130:133], v[202:205], v[62:65]
	v_mfma_i32_16x16x64_i8 v[30:33], v[162:165], v[202:205], v[30:33]
	v_mfma_i32_16x16x64_i8 v[58:61], v[130:133], v[210:213], v[58:61]
	v_mfma_i32_16x16x64_i8 v[26:29], v[162:165], v[210:213], v[26:29]
	v_mfma_i32_16x16x64_i8 v[54:57], v[134:137], v[190:193], v[54:57]
	v_mfma_i32_16x16x64_i8 v[18:21], v[166:169], v[190:193], v[18:21]
	v_mfma_i32_16x16x64_i8 v[50:53], v[134:137], v[198:201], v[50:53]
	v_mfma_i32_16x16x64_i8 v[22:25], v[166:169], v[198:201], v[22:25]
	v_mfma_i32_16x16x64_i8 v[62:65], v[134:137], v[206:209], v[62:65]
	v_mfma_i32_16x16x64_i8 v[30:33], v[166:169], v[206:209], v[30:33]
	v_mfma_i32_16x16x64_i8 v[58:61], v[134:137], v[214:217], v[58:61]
	v_mfma_i32_16x16x64_i8 v[26:29], v[166:169], v[214:217], v[26:29]
	v_mfma_i32_16x16x64_i8 v[46:49], v[170:173], v[186:189], v[46:49]
	v_mfma_i32_16x16x64_i8 v[14:17], v[178:181], v[186:189], v[14:17]
	v_mfma_i32_16x16x64_i8 v[42:45], v[170:173], v[194:197], v[42:45]
	v_mfma_i32_16x16x64_i8 v[10:13], v[178:181], v[194:197], v[10:13]
	v_mfma_i32_16x16x64_i8 v[38:41], v[170:173], v[202:205], v[38:41]
	v_mfma_i32_16x16x64_i8 v[6:9], v[178:181], v[202:205], v[6:9]
	v_mfma_i32_16x16x64_i8 v[34:37], v[170:173], v[210:213], v[34:37]
	v_mfma_i32_16x16x64_i8 v[2:5], v[178:181], v[210:213], v[2:5]
	v_mfma_i32_16x16x64_i8 v[46:49], v[174:177], v[190:193], v[46:49]
	v_mfma_i32_16x16x64_i8 v[14:17], v[182:185], v[190:193], v[14:17]
	v_mfma_i32_16x16x64_i8 v[42:45], v[174:177], v[198:201], v[42:45]
	v_mfma_i32_16x16x64_i8 v[10:13], v[182:185], v[198:201], v[10:13]
	v_mfma_i32_16x16x64_i8 v[38:41], v[174:177], v[206:209], v[38:41]
	v_mfma_i32_16x16x64_i8 v[6:9], v[182:185], v[206:209], v[6:9]
	v_mfma_i32_16x16x64_i8 v[34:37], v[174:177], v[214:217], v[34:37]
	v_mfma_i32_16x16x64_i8 v[2:5], v[182:185], v[214:217], v[2:5]
	s_barrier
	s_add_i32 s93, s93, 2
	s_add_u32 s91, s91, 0x100
	s_addc_u32 s92, s92, 0
	s_cmp_gt_u32 s93, 29
	s_mov_b64 s[2:3], s[4:5]
	s_cbranch_scc0 .LBB0_2056
	s_and_b64 vcc, exec, s[8:9]
	s_cbranch_vccz .LBB0_2059
	s_barrier

.LBB0_2241:
	ds_read_b128 v[130:133], v212
	ds_read_b128 v[134:137], v212 offset:1024
	ds_read_b128 v[138:141], v212 offset:2048
	ds_read_b128 v[142:145], v212 offset:3072
	ds_read_b128 v[146:149], v213
	ds_read_b128 v[150:153], v213 offset:1024
	ds_read_b128 v[154:157], v213 offset:2048
	ds_read_b128 v[158:161], v213 offset:3072
	s_add_u32 s36, s18, 0x100
	s_addc_u32 s37, s19, 0
	s_cmpk_eq_i32 s71, 0xdc
	s_cselect_b32 s41, s3, s37
	s_cselect_b32 s40, s2, s36
	s_cselect_b32 s39, s35, s70
	s_cselect_b32 s38, s34, s69
	v_lshl_add_u64 v[216:217], s[18:19], 0, v[178:179]
	s_add_i32 m0, s44, 0xc000
	ds_read_b128 v[162:165], v214
	ds_read_b128 v[166:169], v214 offset:1024
	ds_read_b128 v[186:189], v214 offset:2048
	ds_read_b128 v[190:193], v214 offset:3072
	ds_read_b128 v[194:197], v214 offset:4096
	ds_read_b128 v[198:201], v214 offset:5120
	ds_read_b128 v[202:205], v214 offset:6144
	ds_read_b128 v[206:209], v214 offset:7168
	global_load_lds_dwordx4 v[216:217], off
	v_lshl_add_u64 v[216:217], s[18:19], 0, v[180:181]
	s_add_i32 m0, s44, 0xe000
	s_nop 0
	global_load_lds_dwordx4 v[216:217], off
	s_waitcnt vmcnt(8)
	s_waitcnt lgkmcnt(0)
	s_barrier
	s_waitcnt lgkmcnt(0)
	v_mfma_f32_16x16x32_bf16 v[126:129], v[130:133], v[162:165], v[126:129]
	v_mfma_f32_16x16x32_bf16 v[122:125], v[138:141], v[162:165], v[122:125]
	v_mfma_f32_16x16x32_bf16 v[110:113], v[130:133], v[186:189], v[110:113]
	v_mfma_f32_16x16x32_bf16 v[106:109], v[138:141], v[186:189], v[106:109]
	v_mfma_f32_16x16x32_bf16 v[94:97], v[130:133], v[194:197], v[94:97]
	v_mfma_f32_16x16x32_bf16 v[90:93], v[138:141], v[194:197], v[90:93]
	v_mfma_f32_16x16x32_bf16 v[78:81], v[130:133], v[202:205], v[78:81]
	v_mfma_f32_16x16x32_bf16 v[74:77], v[138:141], v[202:205], v[74:77]
	v_mfma_f32_16x16x32_bf16 v[126:129], v[134:137], v[166:169], v[126:129]
	v_mfma_f32_16x16x32_bf16 v[122:125], v[142:145], v[166:169], v[122:125]
	v_mfma_f32_16x16x32_bf16 v[110:113], v[134:137], v[190:193], v[110:113]
	v_mfma_f32_16x16x32_bf16 v[106:109], v[142:145], v[190:193], v[106:109]
	v_mfma_f32_16x16x32_bf16 v[94:97], v[134:137], v[198:201], v[94:97]
	v_mfma_f32_16x16x32_bf16 v[90:93], v[142:145], v[198:201], v[90:93]
	v_mfma_f32_16x16x32_bf16 v[78:81], v[134:137], v[206:209], v[78:81]
	v_mfma_f32_16x16x32_bf16 v[74:77], v[142:145], v[206:209], v[74:77]
	v_mfma_f32_16x16x32_bf16 v[118:121], v[146:149], v[162:165], v[118:121]
	v_mfma_f32_16x16x32_bf16 v[114:117], v[154:157], v[162:165], v[114:117]
	v_mfma_f32_16x16x32_bf16 v[102:105], v[146:149], v[186:189], v[102:105]
	v_mfma_f32_16x16x32_bf16 v[98:101], v[154:157], v[186:189], v[98:101]
	v_mfma_f32_16x16x32_bf16 v[86:89], v[146:149], v[194:197], v[86:89]
	v_mfma_f32_16x16x32_bf16 v[82:85], v[154:157], v[194:197], v[82:85]
	v_mfma_f32_16x16x32_bf16 v[70:73], v[146:149], v[202:205], v[70:73]
	v_mfma_f32_16x16x32_bf16 v[66:69], v[154:157], v[202:205], v[66:69]
	v_mfma_f32_16x16x32_bf16 v[118:121], v[150:153], v[166:169], v[118:121]
	v_mfma_f32_16x16x32_bf16 v[114:117], v[158:161], v[166:169], v[114:117]
	v_mfma_f32_16x16x32_bf16 v[102:105], v[150:153], v[190:193], v[102:105]
	v_mfma_f32_16x16x32_bf16 v[98:101], v[158:161], v[190:193], v[98:101]
	v_mfma_f32_16x16x32_bf16 v[86:89], v[150:153], v[198:201], v[86:89]
	v_mfma_f32_16x16x32_bf16 v[82:85], v[158:161], v[198:201], v[82:85]
	v_mfma_f32_16x16x32_bf16 v[70:73], v[150:153], v[206:209], v[70:73]
	v_mfma_f32_16x16x32_bf16 v[66:69], v[158:161], v[206:209], v[66:69]
	s_barrier
	s_add_i32 s18, s56, s43
	v_lshl_add_u64 v[216:217], s[38:39], 0, v[172:173]
	s_mov_b32 m0, s18
	ds_read_b128 v[162:165], v214 offset:16384
	ds_read_b128 v[166:169], v214 offset:17408
	ds_read_b128 v[186:189], v214 offset:18432
	ds_read_b128 v[190:193], v214 offset:19456
	ds_read_b128 v[194:197], v214 offset:20480
	ds_read_b128 v[198:201], v214 offset:21504
	ds_read_b128 v[202:205], v214 offset:22528
	ds_read_b128 v[206:209], v214 offset:23552
	global_load_lds_dwordx4 v[216:217], off
	s_add_i32 m0, s18, 0x2000
	s_add_u32 s18, s38, 0x380000
	v_lshl_add_u64 v[218:219], s[38:39], 0, v[176:177]
	s_addc_u32 s19, s39, 0
	s_add_i32 s72, s57, s43
	global_load_lds_dwordx4 v[218:219], off
	v_lshl_add_u64 v[220:221], s[18:19], 0, v[172:173]
	s_mov_b32 m0, s72
	v_lshl_add_u64 v[222:223], s[40:41], 0, v[174:175]
	global_load_lds_dwordx4 v[220:221], off
	v_lshl_add_u64 v[220:221], s[18:19], 0, v[176:177]
	s_add_i32 m0, s72, 0x2000
	s_nop 0
	global_load_lds_dwordx4 v[220:221], off
	v_lshl_add_u64 v[220:221], s[40:41], 0, v[170:171]
	s_mov_b32 m0, s44
	s_nop 0
	global_load_lds_dwordx4 v[220:221], off
	s_mov_b32 m0, s45
	s_nop 0
	global_load_lds_dwordx4 v[222:223], off
	s_waitcnt vmcnt(8)
	s_waitcnt lgkmcnt(0)
	s_barrier
	s_waitcnt lgkmcnt(0)
	v_mfma_f32_16x16x32_bf16 v[62:65], v[130:133], v[162:165], v[62:65]
	v_mfma_f32_16x16x32_bf16 v[58:61], v[138:141], v[162:165], v[58:61]
	v_mfma_f32_16x16x32_bf16 v[46:49], v[130:133], v[186:189], v[46:49]
	v_mfma_f32_16x16x32_bf16 v[42:45], v[138:141], v[186:189], v[42:45]
	v_mfma_f32_16x16x32_bf16 v[30:33], v[130:133], v[194:197], v[30:33]
	v_mfma_f32_16x16x32_bf16 v[26:29], v[138:141], v[194:197], v[26:29]
	v_mfma_f32_16x16x32_bf16 v[14:17], v[130:133], v[202:205], v[14:17]
	v_mfma_f32_16x16x32_bf16 v[10:13], v[138:141], v[202:205], v[10:13]
	v_mfma_f32_16x16x32_bf16 v[62:65], v[134:137], v[166:169], v[62:65]
	v_mfma_f32_16x16x32_bf16 v[58:61], v[142:145], v[166:169], v[58:61]
	v_mfma_f32_16x16x32_bf16 v[46:49], v[134:137], v[190:193], v[46:49]
	v_mfma_f32_16x16x32_bf16 v[42:45], v[142:145], v[190:193], v[42:45]
	v_mfma_f32_16x16x32_bf16 v[30:33], v[134:137], v[198:201], v[30:33]
	v_mfma_f32_16x16x32_bf16 v[26:29], v[142:145], v[198:201], v[26:29]
	v_mfma_f32_16x16x32_bf16 v[14:17], v[134:137], v[206:209], v[14:17]
	v_mfma_f32_16x16x32_bf16 v[10:13], v[142:145], v[206:209], v[10:13]
	v_mfma_f32_16x16x32_bf16 v[54:57], v[146:149], v[162:165], v[54:57]
	v_mfma_f32_16x16x32_bf16 v[50:53], v[154:157], v[162:165], v[50:53]
	v_mfma_f32_16x16x32_bf16 v[38:41], v[146:149], v[186:189], v[38:41]
	v_mfma_f32_16x16x32_bf16 v[34:37], v[154:157], v[186:189], v[34:37]
	v_mfma_f32_16x16x32_bf16 v[22:25], v[146:149], v[194:197], v[22:25]
	v_mfma_f32_16x16x32_bf16 v[18:21], v[154:157], v[194:197], v[18:21]
	v_mfma_f32_16x16x32_bf16 v[6:9], v[146:149], v[202:205], v[6:9]
	v_mfma_f32_16x16x32_bf16 v[2:5], v[154:157], v[202:205], v[2:5]
	v_mfma_f32_16x16x32_bf16 v[54:57], v[150:153], v[166:169], v[54:57]
	v_mfma_f32_16x16x32_bf16 v[50:53], v[158:161], v[166:169], v[50:53]
	v_mfma_f32_16x16x32_bf16 v[38:41], v[150:153], v[190:193], v[38:41]
	v_mfma_f32_16x16x32_bf16 v[34:37], v[158:161], v[190:193], v[34:37]
	v_mfma_f32_16x16x32_bf16 v[22:25], v[150:153], v[198:201], v[22:25]
	v_mfma_f32_16x16x32_bf16 v[18:21], v[158:161], v[198:201], v[18:21]
	v_mfma_f32_16x16x32_bf16 v[6:9], v[150:153], v[206:209], v[6:9]
	v_mfma_f32_16x16x32_bf16 v[2:5], v[158:161], v[206:209], v[2:5]
	s_barrier
	s_add_i32 s72, 0, 0x18000
	s_add_i32 s73, 0, 0x1c000
	v_add_u32_e32 v142, s72, v211
	v_add_u32_e32 v158, s73, v211
	ds_read_b128 v[130:133], v142
	ds_read_b128 v[134:137], v142 offset:1024
	ds_read_b128 v[138:141], v142 offset:2048
	ds_read_b128 v[142:145], v142 offset:3072
	ds_read_b128 v[146:149], v158
	ds_read_b128 v[150:153], v158 offset:1024
	ds_read_b128 v[154:157], v158 offset:2048
	ds_read_b128 v[158:161], v158 offset:3072
	s_add_u32 s18, s40, 0x380000
	s_addc_u32 s19, s41, 0
	s_mov_b32 m0, s46
	v_lshl_add_u64 v[224:225], s[18:19], 0, v[170:171]
	ds_read_b128 v[162:165], v214 offset:32768
	ds_read_b128 v[166:169], v214 offset:33792
	ds_read_b128 v[186:189], v214 offset:34816
	ds_read_b128 v[190:193], v214 offset:35840
	ds_read_b128 v[194:197], v214 offset:36864
	ds_read_b128 v[198:201], v214 offset:37888
	ds_read_b128 v[202:205], v214 offset:38912
	ds_read_b128 v[206:209], v214 offset:39936
	global_load_lds_dwordx4 v[224:225], off
	v_lshl_add_u64 v[224:225], s[18:19], 0, v[174:175]
	s_mov_b32 m0, s47
	s_nop 0
	global_load_lds_dwordx4 v[224:225], off
	s_waitcnt vmcnt(8)
	s_waitcnt lgkmcnt(0)
	s_barrier
	s_waitcnt lgkmcnt(0)
	v_mfma_f32_16x16x32_bf16 v[126:129], v[130:133], v[162:165], v[126:129]
	v_mfma_f32_16x16x32_bf16 v[122:125], v[138:141], v[162:165], v[122:125]
	v_mfma_f32_16x16x32_bf16 v[110:113], v[130:133], v[186:189], v[110:113]
	v_mfma_f32_16x16x32_bf16 v[106:109], v[138:141], v[186:189], v[106:109]
	v_mfma_f32_16x16x32_bf16 v[94:97], v[130:133], v[194:197], v[94:97]
	v_mfma_f32_16x16x32_bf16 v[90:93], v[138:141], v[194:197], v[90:93]
	v_mfma_f32_16x16x32_bf16 v[78:81], v[130:133], v[202:205], v[78:81]
	v_mfma_f32_16x16x32_bf16 v[74:77], v[138:141], v[202:205], v[74:77]
	v_mfma_f32_16x16x32_bf16 v[126:129], v[134:137], v[166:169], v[126:129]
	v_mfma_f32_16x16x32_bf16 v[122:125], v[142:145], v[166:169], v[122:125]
	v_mfma_f32_16x16x32_bf16 v[110:113], v[134:137], v[190:193], v[110:113]
	v_mfma_f32_16x16x32_bf16 v[106:109], v[142:145], v[190:193], v[106:109]
	v_mfma_f32_16x16x32_bf16 v[94:97], v[134:137], v[198:201], v[94:97]
	v_mfma_f32_16x16x32_bf16 v[90:93], v[142:145], v[198:201], v[90:93]
	v_mfma_f32_16x16x32_bf16 v[78:81], v[134:137], v[206:209], v[78:81]
	v_mfma_f32_16x16x32_bf16 v[74:77], v[142:145], v[206:209], v[74:77]
	v_mfma_f32_16x16x32_bf16 v[118:121], v[146:149], v[162:165], v[118:121]
	v_mfma_f32_16x16x32_bf16 v[114:117], v[154:157], v[162:165], v[114:117]
	v_mfma_f32_16x16x32_bf16 v[102:105], v[146:149], v[186:189], v[102:105]
	v_mfma_f32_16x16x32_bf16 v[98:101], v[154:157], v[186:189], v[98:101]
	v_mfma_f32_16x16x32_bf16 v[86:89], v[146:149], v[194:197], v[86:89]
	v_mfma_f32_16x16x32_bf16 v[82:85], v[154:157], v[194:197], v[82:85]
	v_mfma_f32_16x16x32_bf16 v[70:73], v[146:149], v[202:205], v[70:73]
	v_mfma_f32_16x16x32_bf16 v[66:69], v[154:157], v[202:205], v[66:69]
	v_mfma_f32_16x16x32_bf16 v[118:121], v[150:153], v[166:169], v[118:121]
	v_mfma_f32_16x16x32_bf16 v[114:117], v[158:161], v[166:169], v[114:117]
	v_mfma_f32_16x16x32_bf16 v[102:105], v[150:153], v[190:193], v[102:105]
	v_mfma_f32_16x16x32_bf16 v[98:101], v[158:161], v[190:193], v[98:101]
	v_mfma_f32_16x16x32_bf16 v[86:89], v[150:153], v[198:201], v[86:89]
	v_mfma_f32_16x16x32_bf16 v[82:85], v[158:161], v[198:201], v[82:85]
	v_mfma_f32_16x16x32_bf16 v[70:73], v[150:153], v[206:209], v[70:73]
	v_mfma_f32_16x16x32_bf16 v[66:69], v[158:161], v[206:209], v[66:69]
	s_barrier
	s_add_i32 s18, s72, s43
	v_lshl_add_u64 v[216:217], v[216:217], 0, s[8:9]
	s_mov_b32 m0, s18
	ds_read_b128 v[162:165], v214 offset:49152
	ds_read_b128 v[166:169], v214 offset:50176
	ds_read_b128 v[186:189], v214 offset:51200
	ds_read_b128 v[190:193], v214 offset:52224
	ds_read_b128 v[194:197], v214 offset:53248
	ds_read_b128 v[198:201], v214 offset:54272
	ds_read_b128 v[202:205], v214 offset:55296
	ds_read_b128 v[206:209], v214 offset:56320
	global_load_lds_dwordx4 v[216:217], off
	s_add_i32 m0, s18, 0x2000
	s_add_u32 s18, s38, 0x380080
	v_lshl_add_u64 v[216:217], v[218:219], 0, s[8:9]
	s_addc_u32 s19, s39, 0
	s_add_i32 s38, s73, s43
	global_load_lds_dwordx4 v[216:217], off
	v_lshl_add_u64 v[216:217], s[18:19], 0, v[172:173]
	s_mov_b32 m0, s38
	s_nop 0
	global_load_lds_dwordx4 v[216:217], off
	v_lshl_add_u64 v[216:217], s[18:19], 0, v[176:177]
	s_add_i32 m0, s38, 0x2000
	s_nop 0
	global_load_lds_dwordx4 v[216:217], off
	v_lshl_add_u64 v[216:217], v[220:221], 0, s[8:9]
	s_mov_b32 m0, s51
	s_nop 0
	global_load_lds_dwordx4 v[216:217], off
	v_lshl_add_u64 v[216:217], v[222:223], 0, s[8:9]
	s_mov_b32 m0, s54
	s_nop 0
	global_load_lds_dwordx4 v[216:217], off
	s_waitcnt vmcnt(8)
	s_waitcnt lgkmcnt(0)
	s_barrier
	s_waitcnt lgkmcnt(0)
	v_mfma_f32_16x16x32_bf16 v[62:65], v[130:133], v[162:165], v[62:65]
	v_mfma_f32_16x16x32_bf16 v[58:61], v[138:141], v[162:165], v[58:61]
	v_mfma_f32_16x16x32_bf16 v[46:49], v[130:133], v[186:189], v[46:49]
	v_mfma_f32_16x16x32_bf16 v[42:45], v[138:141], v[186:189], v[42:45]
	v_mfma_f32_16x16x32_bf16 v[30:33], v[130:133], v[194:197], v[30:33]
	v_mfma_f32_16x16x32_bf16 v[26:29], v[138:141], v[194:197], v[26:29]
	v_mfma_f32_16x16x32_bf16 v[14:17], v[130:133], v[202:205], v[14:17]
	v_mfma_f32_16x16x32_bf16 v[10:13], v[138:141], v[202:205], v[10:13]
	v_mfma_f32_16x16x32_bf16 v[62:65], v[134:137], v[166:169], v[62:65]
	v_mfma_f32_16x16x32_bf16 v[58:61], v[142:145], v[166:169], v[58:61]
	v_mfma_f32_16x16x32_bf16 v[46:49], v[134:137], v[190:193], v[46:49]
	v_mfma_f32_16x16x32_bf16 v[42:45], v[142:145], v[190:193], v[42:45]
	v_mfma_f32_16x16x32_bf16 v[30:33], v[134:137], v[198:201], v[30:33]
	v_mfma_f32_16x16x32_bf16 v[26:29], v[142:145], v[198:201], v[26:29]
	v_mfma_f32_16x16x32_bf16 v[14:17], v[134:137], v[206:209], v[14:17]
	v_mfma_f32_16x16x32_bf16 v[10:13], v[142:145], v[206:209], v[10:13]
	v_mfma_f32_16x16x32_bf16 v[54:57], v[146:149], v[162:165], v[54:57]
	v_mfma_f32_16x16x32_bf16 v[50:53], v[154:157], v[162:165], v[50:53]
	v_mfma_f32_16x16x32_bf16 v[38:41], v[146:149], v[186:189], v[38:41]
	v_mfma_f32_16x16x32_bf16 v[34:37], v[154:157], v[186:189], v[34:37]
	v_mfma_f32_16x16x32_bf16 v[22:25], v[146:149], v[194:197], v[22:25]
	v_mfma_f32_16x16x32_bf16 v[18:21], v[154:157], v[194:197], v[18:21]
	v_mfma_f32_16x16x32_bf16 v[6:9], v[146:149], v[202:205], v[6:9]
	v_mfma_f32_16x16x32_bf16 v[2:5], v[154:157], v[202:205], v[2:5]
	v_mfma_f32_16x16x32_bf16 v[54:57], v[150:153], v[166:169], v[54:57]
	v_mfma_f32_16x16x32_bf16 v[50:53], v[158:161], v[166:169], v[50:53]
	v_mfma_f32_16x16x32_bf16 v[38:41], v[150:153], v[190:193], v[38:41]
	v_mfma_f32_16x16x32_bf16 v[34:37], v[158:161], v[190:193], v[34:37]
	v_mfma_f32_16x16x32_bf16 v[22:25], v[150:153], v[198:201], v[22:25]
	v_mfma_f32_16x16x32_bf16 v[18:21], v[158:161], v[198:201], v[18:21]
	v_mfma_f32_16x16x32_bf16 v[6:9], v[150:153], v[206:209], v[6:9]
	v_mfma_f32_16x16x32_bf16 v[2:5], v[158:161], v[206:209], v[2:5]
	s_barrier
	s_add_i32 s71, s71, 2
	s_add_u32 s69, s69, 0x100
	s_addc_u32 s70, s70, 0
	s_cmpk_gt_u32 s71, 0xdd
	s_mov_b64 s[18:19], s[36:37]
	s_cbranch_scc0 .LBB0_2241
	s_and_b64 vcc, exec, s[10:11]
	s_cbranch_vccz .LBB0_2244
	s_barrier
